# attention: relative-bias table of the head staged in LDS by the workgroup (ds_read instead of 64 global loads per task); packed P converts, fma score/exp forms
# baseline (speedup 1.0000x reference)
.LBB0_456:
	s_andn2_b64 vcc, exec, s[0:1]
	s_cbranch_vccnz .LBB0_720
	s_add_u32 s48, s52, 0x3e5000c8
	s_mov_b32 s37, 0
	s_addc_u32 s49, s53, 0
	s_mov_b32 s36, s37
	s_cmp_lg_u32 0, -1
	s_mov_b32 s38, s37
	s_mov_b32 s39, s37
	v_mov_b64_e32 v[0:1], s[36:37]
	s_cselect_b64 s[50:51], -1, 0
	v_mov_b32_e32 v125, 0
	s_movk_i32 s66, 0x1000
	s_movk_i32 s67, 0x90
	s_movk_i32 s86, 0x210
	s_mov_b64 s[68:69], 0x1000
	v_mov_b32_e32 v131, 0x78
	v_mov_b64_e32 v[2:3], s[38:39]
	s_mov_b32 s87, 0xf149f2ca
	s_mov_b64 s[38:39], 0x32a05ec0
	s_mov_b64 s[70:71], 0x2eac0180
	s_mov_b64 s[72:73], 0x100
	v_mov_b32_e32 v137, 0xf149f2ca
	s_mov_b32 s88, 0
	s_mov_b32 s89, 0
	s_mov_b64 s[74:75], 0x110
	s_mov_b64 s[76:77], 0x140
	s_mov_b64 s[78:79], 0x150
	s_mov_b64 s[80:81], 0x80
	s_mov_b64 s[82:83], 0x200
	global_load_dwordx2 v[4:5], v125, s[48:49]
	s_waitcnt vmcnt(0)
	v_readfirstlane_b32 s48, v4
	v_readfirstlane_b32 s49, v5
	s_branch .LBB0_459
.LBB0_459:
	v_mov_b32_e32 v37, v189
	s_mov_b32 s0, s33
	s_lshl_b32 s1, s0, 8
	s_and_b32 s1, s1, 0x700
	s_add_i32 s1, s1, s0
	s_and_b32 s4, s1, -8
	s_lshl_b32 s0, s89, 11
	s_add_i32 s2, s4, s0
	s_ashr_i32 s1, s2, 13
	s_lshl_b32 s3, s1, 8
	s_add_i32 s3, s3, 0x8000
	v_ashrrev_i32_e32 v46, 3, v37
	v_add_u32_e32 v4, s3, v46
	v_add_u32_e32 v22, 0x200, v37
	v_ashrrev_i32_e32 v5, 31, v4
	v_ashrrev_i32_e32 v48, 3, v22
	s_bfe_u32 s0, s2, 0x40009
	v_lshlrev_b64 v[4:5], 13, v[4:5]
	v_add_u32_e32 v6, s3, v48
	v_add_u32_e32 v28, 0x400, v37
	v_lshlrev_b32_e32 v20, 4, v37
	v_lshl_add_u64 v[4:5], s[60:61], 0, v[4:5]
	s_lshl_b32 s36, s0, 7
	v_ashrrev_i32_e32 v7, 31, v6
	v_ashrrev_i32_e32 v49, 3, v28
	v_and_b32_e32 v124, 0x70, v20
	v_lshl_add_u64 v[4:5], v[4:5], 0, s[36:37]
	v_lshlrev_b64 v[6:7], 13, v[6:7]
	v_add_u32_e32 v12, s3, v49
	v_add_u32_e32 v34, 0x600, v37
	v_lshl_add_u64 v[4:5], v[4:5], 0, v[124:125]
	v_lshl_add_u64 v[6:7], s[60:61], 0, v[6:7]
	v_ashrrev_i32_e32 v13, 31, v12
	v_ashrrev_i32_e32 v50, 3, v34
	v_add_co_u32_e32 v4, vcc, s66, v4
	v_lshl_add_u64 v[6:7], v[6:7], 0, s[36:37]
	v_lshlrev_b64 v[12:13], 13, v[12:13]
	v_add_u32_e32 v14, s3, v50
	v_addc_co_u32_e32 v5, vcc, 0, v5, vcc
	v_lshl_add_u64 v[6:7], v[6:7], 0, v[124:125]
	v_lshl_add_u64 v[12:13], s[60:61], 0, v[12:13]
	v_ashrrev_i32_e32 v15, 31, v14
	v_add_co_u32_e32 v8, vcc, s66, v6
	v_lshl_add_u64 v[12:13], v[12:13], 0, s[36:37]
	v_lshlrev_b64 v[14:15], 13, v[14:15]
	v_addc_co_u32_e32 v9, vcc, 0, v7, vcc
	v_lshl_add_u64 v[12:13], v[12:13], 0, v[124:125]
	v_lshl_add_u64 v[14:15], s[60:61], 0, v[14:15]
	s_lshl_b32 s1, s1, 4
	v_add_co_u32_e32 v12, vcc, s66, v12
	v_lshl_add_u64 v[14:15], v[14:15], 0, s[36:37]
	s_or_b32 s0, s1, s0
	v_addc_co_u32_e32 v13, vcc, 0, v13, vcc
	v_lshl_add_u64 v[14:15], v[14:15], 0, v[124:125]
	s_ashr_i32 s1, s0, 31
	s_barrier
	s_bfe_u32 s5, s2, 0x40009
	s_mul_i32 s5, s5, 0x744
	v_lshlrev_b32_e32 v56, 2, v189
	s_add_u32 s6, s48, s5
	s_addc_u32 s7, s49, 0
	v_cmp_gt_u32_e32 vcc, 0x744, v56
	s_and_saveexec_b64 s[8:9], vcc
	global_load_dword v57, v56, s[6:7]
	s_or_b64 exec, exec, s[8:9]
	global_load_dwordx4 v[4:7], v[4:5], off
	s_nop 0
	global_load_dwordx4 v[8:11], v[8:9], off
	v_add_co_u32_e32 v16, vcc, s66, v14
	s_lshl_b64 s[0:1], s[0:1], 15
	s_nop 0
	v_addc_co_u32_e32 v17, vcc, 0, v15, vcc
	s_add_u32 s0, s46, s0
	v_ashrrev_i32_e32 v38, 5, v37
	v_ashrrev_i32_e32 v40, 5, v22
	v_add_u32_e32 v36, 0, v124
	global_load_dwordx4 v[12:15], v[12:13], off
	s_nop 0
	global_load_dwordx4 v[16:19], v[16:17], off
	s_addc_u32 s1, s47, s1
	v_and_b32_e32 v124, 0x1f0, v20
	v_ashrrev_i32_e32 v39, 31, v38
	v_ashrrev_i32_e32 v41, 31, v40
	v_ashrrev_i32_e32 v42, 5, v28
	v_ashrrev_i32_e32 v44, 5, v34
	v_lshl_add_u64 v[32:33], s[0:1], 0, v[124:125]
	v_lshlrev_b64 v[20:21], 9, v[38:39]
	v_lshlrev_b64 v[22:23], 9, v[40:41]
	v_ashrrev_i32_e32 v43, 31, v42
	v_ashrrev_i32_e32 v45, 31, v44
	v_lshl_add_u64 v[20:21], v[32:33], 0, v[20:21]
	v_lshl_add_u64 v[24:25], v[32:33], 0, v[22:23]
	v_lshlrev_b64 v[28:29], 9, v[42:43]
	v_lshlrev_b64 v[34:35], 9, v[44:45]
	global_load_dwordx4 v[20:23], v[20:21], off
	s_nop 0
	global_load_dwordx4 v[24:27], v[24:25], off
	v_lshl_add_u64 v[28:29], v[32:33], 0, v[28:29]
	v_lshl_add_u64 v[32:33], v[32:33], 0, v[34:35]
	global_load_dwordx4 v[28:31], v[28:29], off
	v_mad_u64_u32 v[46:47], s[0:1], v46, s67, v[36:37]
	global_load_dwordx4 v[32:35], v[32:33], off
	v_mov_b32_e32 v129, v125
	v_mov_b32_e32 v141, v125
	v_mov_b32_e32 v139, v125
	v_mov_b32_e32 v39, v125
	s_add_i32 s4, s4, s88
	v_mov_b32_e32 v47, v125
	s_mov_b32 s36, 1
	s_mov_b32 s90, 0
	v_mov_b32_e32 v170, 0xf149f2ca
	v_mov_b32_e32 v171, 0xf149f2ca
	v_mov_b32_e32 v172, 0xf149f2ca
	v_mov_b32_e32 v198, 0xf149f2ca
	s_mov_b32 s91, 0
	v_mov_b32_e32 v152, v125
	v_mov_b32_e32 v153, v125
	v_mov_b32_e32 v154, v125
	v_mov_b32_e32 v155, v125
	s_waitcnt vmcnt(7)
	ds_write_b128 v46, v[4:7] offset:20480
	v_mad_u64_u32 v[4:5], s[0:1], v48, s67, v[36:37]
	s_waitcnt vmcnt(6)
	ds_write_b128 v4, v[8:11] offset:20480
	v_mad_u64_u32 v[4:5], s[0:1], v49, s67, v[36:37]
	s_waitcnt vmcnt(5)
	ds_write_b128 v4, v[12:15] offset:20480
	v_mad_u64_u32 v[4:5], s[0:1], v50, s67, v[36:37]
	s_waitcnt vmcnt(4)
	ds_write_b128 v4, v[16:19] offset:20480
	v_add_u32_e32 v4, 0, v124
	v_mad_u64_u32 v[6:7], s[0:1], v38, s86, v[4:5]
	v_ashrrev_i32_e32 v50, 6, v37
	s_waitcnt vmcnt(3)
	ds_write_b128 v6, v[20:23] offset:57344
	v_mad_u64_u32 v[6:7], s[0:1], v40, s86, v[4:5]
	s_waitcnt vmcnt(2)
	ds_write_b128 v6, v[24:27] offset:57344
	v_mad_u64_u32 v[6:7], s[0:1], v42, s86, v[4:5]
	v_mad_u64_u32 v[4:5], s[0:1], v44, s86, v[4:5]
	s_waitcnt vmcnt(1)
	ds_write_b128 v6, v[28:31] offset:57344
	s_waitcnt vmcnt(0)
	ds_write_b128 v4, v[32:35] offset:57344
	v_add_u32_e32 v4, s2, v50
	s_movk_i32 s0, 0xa00
	v_mul_lo_u32 v5, v50, s0
	v_ashrrev_i32_e32 v44, 13, v4
	v_add_u32_e32 v51, 0, v5
	v_mov_b32_e32 v5, v189
	v_ashrrev_i32_e32 v45, 31, v44
	v_lshlrev_b32_e32 v6, 4, v50
	v_cmp_gt_u32_e32 vcc, 0x744, v56
	v_add_u32_e32 v58, 0x16400, v56
	s_and_saveexec_b64 s[8:9], vcc
	ds_write_b32 v58, v57
	s_or_b64 exec, exec, s[8:9]
	s_waitcnt lgkmcnt(0)
	s_barrier
	v_and_b32_e32 v127, 15, v189
	v_bfe_u32 v128, v189, 4, 2
	v_lshrrev_b32_e32 v209, 6, v189
	v_mov_b32_e32 v213, 0
	v_mov_b32_e32 v218, 0x3e000000
	v_mov_b32_e32 v222, 0x3fb8aa3b
	s_add_u32 s8, s52, 0x3e5000c8
	s_addc_u32 s9, s53, 0
	v_readfirstlane_b32 s0, v209
	v_lshlrev_b32_e32 v130, 13, v127
	v_lshlrev_b32_e32 v210, 4, v128
	v_mov_b32_e32 v211, s8
	v_mov_b32_e32 v212, s9
	s_nop 0
	v_add_u32_e32 v130, v130, v210
	v_lshlrev_b32_e32 v214, 14, v127
	v_add_u32_e32 v214, v214, v210
	v_add_u32_e32 v215, 0x40000, v214
	v_add_u32_e32 v216, 0x80000, v214
	v_add_u32_e32 v217, 0xc0000, v214
	v_mul_u32_u24_e32 v136, 144, v127
	v_add_u32_e32 v136, v136, v210
	v_add_u32_e32 v136, 0x5000, v136
	v_mul_u32_u24_e32 v138, 0x210, v127
	v_add_u32_e32 v138, v138, v210
	v_add_u32_e32 v138, 0xe000, v138
	s_mul_i32 s10, s0, 0xa00
	v_mul_u32_u24_e32 v188, 0x280, v128
	v_lshl_add_u32 v188, v127, 1, v188
	v_add_u32_e32 v188, s10, v188
	v_mul_u32_u24_e32 v191, 160, v127
	v_add_u32_e32 v191, v191, v210
	v_add_u32_e32 v191, s10, v191
	v_lshlrev_b32_e32 v208, 14, v128
	v_lshl_add_u32 v208, v127, 1, v208
	s_add_u32 s0, s0, s2
	s_and_b32 s1, s0, 3
	s_bfe_u32 s3, s0, 0x70002
	s_bfe_u32 s4, s0, 0x40009
	s_lshr_b32 s5, s0, 13
	s_sub_u32 s6, s3, 4
	s_max_i32 s6, s6, 0
	s_min_i32 s6, s6, 0x78
	s_lshl_b32 s7, s1, 4
	s_sub_u32 s7, s7, 8
	s_max_i32 s7, s7, 0
	s_min_i32 s7, s7, 32
	s_lshl_b32 s8, s5, 26
	s_lshl_b32 s9, s4, 7
	s_add_u32 s8, s8, s9
	s_add_u32 s16, s60, s8
	s_addc_u32 s17, s61, 0
	s_lshl_b32 s8, s3, 6
	s_lshl_b32 s9, s1, 4
	s_add_u32 s8, s8, s9
	s_lshl_b32 s9, s8, 13
	s_add_u32 s9, s9, 0x800
	s_add_u32 s14, s16, s9
	s_addc_u32 s15, s17, 0
	global_load_dwordx4 v[4:7], v130, s[14:15]
	global_load_dwordx4 v[8:11], v130, s[14:15] offset:64
	s_lshl_b32 s9, s5, 13
	s_add_u32 s8, s8, s9
	s_lshl_b32 s8, s8, 12
	s_lshl_b32 s9, s4, 7
	s_add_u32 s8, s8, s9
	s_add_u32 s8, s8, 0x34c00800
	s_add_u32 s20, s52, s8
	s_addc_u32 s21, s53, 0
	s_add_u32 s16, s16, 0x1000
	s_addc_u32 s17, s17, 0
	s_lshl_b32 s8, s5, 4
	s_add_u32 s8, s8, s4
	s_lshl_b32 s8, s8, 20
	s_add_u32 s8, s8, 0x2ea00000
	s_add_u32 s18, s52, s8
	s_addc_u32 s19, s53, 0
	s_add_u32 s8, s6, 0
	s_lshl_b32 s8, s8, 6
	s_add_u32 s8, s8, s7
	s_lshl_b32 s8, s8, 13
	s_add_u32 s22, s16, s8
	s_addc_u32 s23, s17, 0
	global_load_dwordx4 v[12:15], v130, s[22:23]
	global_load_dwordx4 v[16:19], v130, s[22:23] offset:64
	s_add_u32 s8, s6, 0
	s_lshl_b32 s8, s8, 6
	s_add_u32 s8, s8, s7
	s_add_u32 s8, s8, 16
	s_lshl_b32 s8, s8, 13
	s_add_u32 s22, s16, s8
	s_addc_u32 s23, s17, 0
	global_load_dwordx4 v[20:23], v130, s[22:23]
	global_load_dwordx4 v[24:27], v130, s[22:23] offset:64
	s_add_u32 s8, s6, 1
	s_lshl_b32 s8, s8, 6
	s_add_u32 s8, s8, s7
	s_lshl_b32 s8, s8, 13
	s_add_u32 s22, s16, s8
	s_addc_u32 s23, s17, 0
	global_load_dwordx4 v[28:31], v130, s[22:23]
	global_load_dwordx4 v[32:35], v130, s[22:23] offset:64
	s_add_u32 s8, s6, 1
	s_lshl_b32 s8, s8, 6
	s_add_u32 s8, s8, s7
	s_add_u32 s8, s8, 16
	s_lshl_b32 s8, s8, 13
	s_add_u32 s22, s16, s8
	s_addc_u32 s23, s17, 0
	global_load_dwordx4 v[36:39], v130, s[22:23]
	global_load_dwordx4 v[40:43], v130, s[22:23] offset:64
	s_sub_u32 s11, s6, s3
	s_add_u32 s11, s11, 7
	s_mul_i32 s11, s11, 124
	s_add_u32 s11, s11, 0x16400
	v_lshlrev_b32_e32 v209, 2, v128
	v_sub_u32_e32 v209, v127, v209
	s_lshl_b32 s8, s1, 4
	s_sub_i32 s9, s7, s8
	s_add_i32 s9, s9, 15
	v_add_u32_e32 v210, s9, v209
	v_med3_i32 v210, v210, 0, 30
	v_lshl_add_u32 v192, v210, 2, s11
	v_lshlrev_b32_e32 v210, 2, v128
	v_add_u32_e32 v210, s8, v210
	v_add_u32_e32 v210, -8, v210
	v_med3_i32 v210, v210, 0, 48
	v_add_u32_e32 v211, s7, v127
	v_sub_u32_e32 v211, v211, v210
	v_mov_b32_e32 v212, 0xf149f2ca
	v_cmp_gt_u32_e32 vcc, 16, v211
	s_nop 1
	v_cndmask_b32_e32 v200, v212, v213, vcc
	v_lshlrev_b32_e32 v209, 2, v128
	v_sub_u32_e32 v209, v127, v209
	s_lshl_b32 s8, s1, 4
	s_sub_i32 s9, s7, s8
	s_add_i32 s9, s9, 14
	v_add_u32_e32 v210, s9, v209
	v_med3_i32 v210, v210, 0, 30
	v_lshl_add_u32 v193, v210, 2, s11
	v_lshlrev_b32_e32 v210, 2, v128
	v_add_u32_e32 v210, s8, v210
	v_add_u32_e32 v210, -7, v210
	v_med3_i32 v210, v210, 0, 48
	v_add_u32_e32 v211, s7, v127
	v_sub_u32_e32 v211, v211, v210
	v_mov_b32_e32 v212, 0xf149f2ca
	v_cmp_gt_u32_e32 vcc, 16, v211
	s_nop 1
	v_cndmask_b32_e32 v201, v212, v213, vcc
	v_lshlrev_b32_e32 v209, 2, v128
	v_sub_u32_e32 v209, v127, v209
	s_lshl_b32 s8, s1, 4
	s_sub_i32 s9, s7, s8
	s_add_i32 s9, s9, 13
	v_add_u32_e32 v210, s9, v209
	v_med3_i32 v210, v210, 0, 30
	v_lshl_add_u32 v194, v210, 2, s11
	v_lshlrev_b32_e32 v210, 2, v128
	v_add_u32_e32 v210, s8, v210
	v_add_u32_e32 v210, -6, v210
	v_med3_i32 v210, v210, 0, 48
	v_add_u32_e32 v211, s7, v127
	v_sub_u32_e32 v211, v211, v210
	v_mov_b32_e32 v212, 0xf149f2ca
	v_cmp_gt_u32_e32 vcc, 16, v211
	s_nop 1
	v_cndmask_b32_e32 v202, v212, v213, vcc
	v_lshlrev_b32_e32 v209, 2, v128
	v_sub_u32_e32 v209, v127, v209
	s_lshl_b32 s8, s1, 4
	s_sub_i32 s9, s7, s8
	s_add_i32 s9, s9, 12
	v_add_u32_e32 v210, s9, v209
	v_med3_i32 v210, v210, 0, 30
	v_lshl_add_u32 v195, v210, 2, s11
	v_lshlrev_b32_e32 v210, 2, v128
	v_add_u32_e32 v210, s8, v210
	v_add_u32_e32 v210, -5, v210
	v_med3_i32 v210, v210, 0, 48
	v_add_u32_e32 v211, s7, v127
	v_sub_u32_e32 v211, v211, v210
	v_mov_b32_e32 v212, 0xf149f2ca
	v_cmp_gt_u32_e32 vcc, 16, v211
	s_nop 1
	v_cndmask_b32_e32 v203, v212, v213, vcc
	v_lshlrev_b32_e32 v209, 2, v128
	v_sub_u32_e32 v209, v127, v209
	s_lshl_b32 s8, s1, 4
	s_sub_i32 s9, s7, s8
	s_add_i32 s9, s9, 31
	v_add_u32_e32 v210, s9, v209
	v_med3_i32 v210, v210, 0, 30
	v_lshl_add_u32 v196, v210, 2, s11
	v_lshlrev_b32_e32 v210, 2, v128
	v_add_u32_e32 v210, s8, v210
	v_add_u32_e32 v210, -8, v210
	v_med3_i32 v210, v210, 0, 48
	v_add_u32_e32 v211, s7, v127
	v_add_u32_e32 v211, 16, v211
	v_sub_u32_e32 v211, v211, v210
	v_mov_b32_e32 v212, 0xf149f2ca
	v_cmp_gt_u32_e32 vcc, 16, v211
	s_nop 1
	v_cndmask_b32_e32 v204, v212, v213, vcc
	v_lshlrev_b32_e32 v209, 2, v128
	v_sub_u32_e32 v209, v127, v209
	s_lshl_b32 s8, s1, 4
	s_sub_i32 s9, s7, s8
	s_add_i32 s9, s9, 30
	v_add_u32_e32 v210, s9, v209
	v_med3_i32 v210, v210, 0, 30
	v_lshl_add_u32 v197, v210, 2, s11
	v_lshlrev_b32_e32 v210, 2, v128
	v_add_u32_e32 v210, s8, v210
	v_add_u32_e32 v210, -7, v210
	v_med3_i32 v210, v210, 0, 48
	v_add_u32_e32 v211, s7, v127
	v_add_u32_e32 v211, 16, v211
	v_sub_u32_e32 v211, v211, v210
	v_mov_b32_e32 v212, 0xf149f2ca
	v_cmp_gt_u32_e32 vcc, 16, v211
	s_nop 1
	v_cndmask_b32_e32 v205, v212, v213, vcc
	v_lshlrev_b32_e32 v209, 2, v128
	v_sub_u32_e32 v209, v127, v209
	s_lshl_b32 s8, s1, 4
	s_sub_i32 s9, s7, s8
	s_add_i32 s9, s9, 29
	v_add_u32_e32 v210, s9, v209
	v_med3_i32 v210, v210, 0, 30
	v_lshl_add_u32 v198, v210, 2, s11
	v_lshlrev_b32_e32 v210, 2, v128
	v_add_u32_e32 v210, s8, v210
	v_add_u32_e32 v210, -6, v210
	v_med3_i32 v210, v210, 0, 48
	v_add_u32_e32 v211, s7, v127
	v_add_u32_e32 v211, 16, v211
	v_sub_u32_e32 v211, v211, v210
	v_mov_b32_e32 v212, 0xf149f2ca
	v_cmp_gt_u32_e32 vcc, 16, v211
	s_nop 1
	v_cndmask_b32_e32 v206, v212, v213, vcc
	v_lshlrev_b32_e32 v209, 2, v128
	v_sub_u32_e32 v209, v127, v209
	s_lshl_b32 s8, s1, 4
	s_sub_i32 s9, s7, s8
	s_add_i32 s9, s9, 28
	v_add_u32_e32 v210, s9, v209
	v_med3_i32 v210, v210, 0, 30
	v_lshl_add_u32 v199, v210, 2, s11
	v_lshlrev_b32_e32 v210, 2, v128
	v_add_u32_e32 v210, s8, v210
	v_add_u32_e32 v210, -5, v210
	v_med3_i32 v210, v210, 0, 48
	v_add_u32_e32 v211, s7, v127
	v_add_u32_e32 v211, 16, v211
	v_sub_u32_e32 v211, v211, v210
	v_mov_b32_e32 v212, 0xf149f2ca
	v_cmp_gt_u32_e32 vcc, 16, v211
	s_nop 1
	v_cndmask_b32_e32 v207, v212, v213, vcc
	v_mov_b32_e32 v172, 0xf149f2ca
	v_mov_b32_e32 v176, 0
	v_mov_b32_e32 v173, 0xf149f2ca
	v_mov_b32_e32 v177, 0
	v_mov_b32_e32 v174, 0xf149f2ca
	v_mov_b32_e32 v178, 0
	v_mov_b32_e32 v175, 0xf149f2ca
	v_mov_b32_e32 v179, 0
	v_mov_b32_e32 v100, 0
	v_mov_b32_e32 v101, 0
	v_mov_b32_e32 v102, 0
	v_mov_b32_e32 v103, 0
	v_mov_b32_e32 v132, 0
	v_mov_b32_e32 v133, 0
	v_mov_b32_e32 v134, 0
	v_mov_b32_e32 v135, 0
	v_mov_b32_e32 v140, 0
	v_mov_b32_e32 v141, 0
	v_mov_b32_e32 v142, 0
	v_mov_b32_e32 v143, 0
	v_mov_b32_e32 v144, 0
	v_mov_b32_e32 v145, 0
	v_mov_b32_e32 v146, 0
	v_mov_b32_e32 v147, 0
	ds_read_b32 v148, v192 offset:0
	ds_read_b32 v149, v193 offset:0
	ds_read_b32 v150, v194 offset:0
	ds_read_b32 v151, v195 offset:0
	ds_read_b32 v152, v196 offset:0
	ds_read_b32 v153, v197 offset:0
	ds_read_b32 v154, v198 offset:0
	ds_read_b32 v155, v199 offset:0
	ds_read_b32 v156, v192 offset:124
	ds_read_b32 v157, v193 offset:124
	ds_read_b32 v158, v194 offset:124
	ds_read_b32 v159, v195 offset:124
	ds_read_b32 v160, v196 offset:124
	ds_read_b32 v161, v197 offset:124
	ds_read_b32 v162, v198 offset:124
	ds_read_b32 v163, v199 offset:124
	s_add_u32 s8, s6, 0
	s_lshl_b32 s8, s8, 6
	s_add_u32 s8, s8, s7
	s_lshl_b32 s8, s8, 1
	s_add_u32 s24, s18, s8
	s_addc_u32 s25, s19, 0
	global_load_dwordx4 v[44:47], v214, s[24:25]
	global_load_dwordx4 v[48:51], v215, s[24:25]
	global_load_dwordx4 v[52:55], v216, s[24:25]
	global_load_dwordx4 v[56:59], v217, s[24:25]
	s_add_u32 s8, s6, 1
	s_lshl_b32 s8, s8, 6
	s_add_u32 s8, s8, s7
	s_lshl_b32 s8, s8, 1
	s_add_u32 s24, s18, s8
	s_addc_u32 s25, s19, 0
	global_load_dwordx4 v[60:63], v214, s[24:25]
	global_load_dwordx4 v[64:67], v215, s[24:25]
	global_load_dwordx4 v[68:71], v216, s[24:25]
	global_load_dwordx4 v[72:75], v217, s[24:25]
	s_waitcnt vmcnt(8)
	v_mfma_f32_16x16x32_bf16 v[76:79], v[4:7], v[12:15], 0
	v_mfma_f32_16x16x32_bf16 v[76:79], v[8:11], v[16:19], v[76:79]
	v_mfma_f32_16x16x32_bf16 v[84:87], v[4:7], v[20:23], 0
	v_mfma_f32_16x16x32_bf16 v[84:87], v[8:11], v[24:27], v[84:87]
	v_mfma_f32_16x16x32_bf16 v[88:91], v[4:7], v[28:31], 0
	v_mfma_f32_16x16x32_bf16 v[88:91], v[8:11], v[32:35], v[88:91]
	v_mfma_f32_16x16x32_bf16 v[96:99], v[4:7], v[36:39], 0
	v_mfma_f32_16x16x32_bf16 v[96:99], v[8:11], v[40:43], v[96:99]
	s_add_u32 s8, s6, 2
	s_lshl_b32 s8, s8, 6
	s_add_u32 s8, s8, s7
	s_lshl_b32 s8, s8, 13
	s_add_u32 s22, s16, s8
	s_addc_u32 s23, s17, 0
	global_load_dwordx4 v[12:15], v130, s[22:23]
	global_load_dwordx4 v[16:19], v130, s[22:23] offset:64
	s_add_u32 s8, s6, 2
	s_lshl_b32 s8, s8, 6
	s_add_u32 s8, s8, s7
	s_add_u32 s8, s8, 16
	s_lshl_b32 s8, s8, 13
	s_add_u32 s22, s16, s8
	s_addc_u32 s23, s17, 0
	global_load_dwordx4 v[20:23], v130, s[22:23]
	global_load_dwordx4 v[24:27], v130, s[22:23] offset:64
	s_add_u32 s8, s6, 3
	s_lshl_b32 s8, s8, 6
	s_add_u32 s8, s8, s7
	s_lshl_b32 s8, s8, 13
	s_add_u32 s22, s16, s8
	s_addc_u32 s23, s17, 0
	global_load_dwordx4 v[28:31], v130, s[22:23]
	global_load_dwordx4 v[32:35], v130, s[22:23] offset:64
	s_add_u32 s8, s6, 3
	s_lshl_b32 s8, s8, 6
	s_add_u32 s8, s8, s7
	s_add_u32 s8, s8, 16
	s_lshl_b32 s8, s8, 13
	s_add_u32 s22, s16, s8
	s_addc_u32 s23, s17, 0
	global_load_dwordx4 v[36:39], v130, s[22:23]
	global_load_dwordx4 v[40:43], v130, s[22:23] offset:64
	s_nop 7
	s_waitcnt lgkmcnt(0)
	v_add_f32_e32 v148, v148, v200
	v_fma_f32 v76, v76, v218, v148
	v_add_f32_e32 v149, v149, v201
	v_fma_f32 v77, v77, v218, v149
	v_add_f32_e32 v150, v150, v202
	v_fma_f32 v78, v78, v218, v150
	v_add_f32_e32 v151, v151, v203
	v_fma_f32 v79, v79, v218, v151
	v_add_f32_e32 v152, v152, v204
	v_fma_f32 v84, v84, v218, v152
	v_add_f32_e32 v153, v153, v205
	v_fma_f32 v85, v85, v218, v153
	v_add_f32_e32 v154, v154, v206
	v_fma_f32 v86, v86, v218, v154
	v_add_f32_e32 v155, v155, v207
	v_fma_f32 v87, v87, v218, v155
	v_add_f32_e32 v156, v156, v200
	v_fma_f32 v88, v88, v218, v156
	v_add_f32_e32 v157, v157, v201
	v_fma_f32 v89, v89, v218, v157
	v_add_f32_e32 v158, v158, v202
	v_fma_f32 v90, v90, v218, v158
	v_add_f32_e32 v159, v159, v203
	v_fma_f32 v91, v91, v218, v159
	v_add_f32_e32 v160, v160, v204
	v_fma_f32 v96, v96, v218, v160
	v_add_f32_e32 v161, v161, v205
	v_fma_f32 v97, v97, v218, v161
	v_add_f32_e32 v162, v162, v206
	v_fma_f32 v98, v98, v218, v162
	v_add_f32_e32 v163, v163, v207
	v_fma_f32 v99, v99, v218, v163
	v_max3_f32 v184, v76, v84, v88
	v_max_f32_e32 v184, v184, v96
	v_max3_f32 v185, v77, v85, v89
	v_max_f32_e32 v185, v185, v97
	v_max3_f32 v186, v78, v86, v90
	v_max_f32_e32 v186, v186, v98
	v_max3_f32 v187, v79, v87, v91
	v_max_f32_e32 v187, v187, v99
	s_nop 0
	v_max_f32_dpp v184, v184, v184 quad_perm:[1,0,3,2] row_mask:0xf bank_mask:0xf
	v_max_f32_dpp v185, v185, v185 quad_perm:[1,0,3,2] row_mask:0xf bank_mask:0xf
	v_max_f32_dpp v186, v186, v186 quad_perm:[1,0,3,2] row_mask:0xf bank_mask:0xf
	v_max_f32_dpp v187, v187, v187 quad_perm:[1,0,3,2] row_mask:0xf bank_mask:0xf
	v_max_f32_dpp v184, v184, v184 quad_perm:[2,3,0,1] row_mask:0xf bank_mask:0xf
	v_max_f32_dpp v185, v185, v185 quad_perm:[2,3,0,1] row_mask:0xf bank_mask:0xf
	v_max_f32_dpp v186, v186, v186 quad_perm:[2,3,0,1] row_mask:0xf bank_mask:0xf
	v_max_f32_dpp v187, v187, v187 quad_perm:[2,3,0,1] row_mask:0xf bank_mask:0xf
	v_max_f32_dpp v184, v184, v184 row_half_mirror row_mask:0xf bank_mask:0xf
	v_max_f32_dpp v185, v185, v185 row_half_mirror row_mask:0xf bank_mask:0xf
	v_max_f32_dpp v186, v186, v186 row_half_mirror row_mask:0xf bank_mask:0xf
	v_max_f32_dpp v187, v187, v187 row_half_mirror row_mask:0xf bank_mask:0xf
	v_max_f32_dpp v184, v184, v184 row_ror:8 row_mask:0xf bank_mask:0xf
	v_max_f32_dpp v185, v185, v185 row_ror:8 row_mask:0xf bank_mask:0xf
	v_max_f32_dpp v186, v186, v186 row_ror:8 row_mask:0xf bank_mask:0xf
	v_max_f32_dpp v187, v187, v187 row_ror:8 row_mask:0xf bank_mask:0xf
	v_max_f32_e32 v184, v172, v184
	v_max_f32_e32 v185, v173, v185
	v_max_f32_e32 v186, v174, v186
	v_max_f32_e32 v187, v175, v187
	v_sub_f32_e32 v180, v172, v184
	v_mov_b32_e32 v172, v184
	v_sub_f32_e32 v181, v173, v185
	v_mov_b32_e32 v173, v185
	v_sub_f32_e32 v182, v174, v186
	v_mov_b32_e32 v174, v186
	v_sub_f32_e32 v183, v175, v187
	v_mov_b32_e32 v175, v187
	v_mul_f32_e32 v180, 0x3fb8aa3b, v180
	v_mul_f32_e32 v181, 0x3fb8aa3b, v181
	v_mul_f32_e32 v182, 0x3fb8aa3b, v182
	v_mul_f32_e32 v183, 0x3fb8aa3b, v183
	v_exp_f32_e32 v180, v180
	v_exp_f32_e32 v181, v181
	v_exp_f32_e32 v182, v182
	v_exp_f32_e32 v183, v183
	v_mul_f32_e32 v184, 0x3fb8aa3b, v172
	v_mul_f32_e32 v185, 0x3fb8aa3b, v173
	v_mul_f32_e32 v186, 0x3fb8aa3b, v174
	v_mul_f32_e32 v187, 0x3fb8aa3b, v175
	v_fma_f32 v76, v76, v222, -v184
	v_fma_f32 v77, v77, v222, -v185
	v_fma_f32 v78, v78, v222, -v186
	v_fma_f32 v79, v79, v222, -v187
	v_fma_f32 v84, v84, v222, -v184
	v_fma_f32 v85, v85, v222, -v185
	v_fma_f32 v86, v86, v222, -v186
	v_fma_f32 v87, v87, v222, -v187
	v_fma_f32 v88, v88, v222, -v184
	v_fma_f32 v89, v89, v222, -v185
	v_fma_f32 v90, v90, v222, -v186
	v_fma_f32 v91, v91, v222, -v187
	v_fma_f32 v96, v96, v222, -v184
	v_fma_f32 v97, v97, v222, -v185
	v_fma_f32 v98, v98, v222, -v186
	v_fma_f32 v99, v99, v222, -v187
	v_exp_f32_e32 v76, v76
	v_exp_f32_e32 v77, v77
	v_exp_f32_e32 v78, v78
	v_exp_f32_e32 v79, v79
	v_exp_f32_e32 v84, v84
	v_exp_f32_e32 v85, v85
	v_exp_f32_e32 v86, v86
	v_exp_f32_e32 v87, v87
	v_exp_f32_e32 v88, v88
	v_exp_f32_e32 v89, v89
	v_exp_f32_e32 v90, v90
	v_exp_f32_e32 v91, v91
	v_exp_f32_e32 v96, v96
	v_exp_f32_e32 v97, v97
	v_exp_f32_e32 v98, v98
	v_exp_f32_e32 v99, v99
	s_nop 0
	v_mul_f32_e32 v176, v176, v180
	v_mul_f32_e32 v177, v177, v181
	v_mul_f32_e32 v178, v178, v182
	v_mul_f32_e32 v179, v179, v183
	v_add_f32_e32 v176, v176, v76
	v_add_f32_e32 v177, v177, v77
	v_add_f32_e32 v178, v178, v78
	v_add_f32_e32 v179, v179, v79
	v_add_f32_e32 v176, v176, v84
	v_add_f32_e32 v177, v177, v85
	v_add_f32_e32 v178, v178, v86
	v_add_f32_e32 v179, v179, v87
	v_add_f32_e32 v176, v176, v88
	v_add_f32_e32 v177, v177, v89
	v_add_f32_e32 v178, v178, v90
	v_add_f32_e32 v179, v179, v91
	v_add_f32_e32 v176, v176, v96
	v_add_f32_e32 v177, v177, v97
	v_add_f32_e32 v178, v178, v98
	v_add_f32_e32 v179, v179, v99
	v_cvt_pk_bf16_f32 v80, v76, v84
	ds_write_b16 v188, v80 offset:0
	ds_write_b16_d16_hi v188, v80 offset:32
	v_cvt_pk_bf16_f32 v81, v77, v85
	ds_write_b16 v188, v81 offset:160
	ds_write_b16_d16_hi v188, v81 offset:192
	v_cvt_pk_bf16_f32 v124, v78, v86
	ds_write_b16 v188, v124 offset:320
	ds_write_b16_d16_hi v188, v124 offset:352
	v_cvt_pk_bf16_f32 v126, v79, v87
	ds_write_b16 v188, v126 offset:480
	ds_write_b16_d16_hi v188, v126 offset:512
	v_cvt_pk_bf16_f32 v80, v88, v96
	ds_write_b16 v188, v80 offset:64
	ds_write_b16_d16_hi v188, v80 offset:96
	v_cvt_pk_bf16_f32 v81, v89, v97
	ds_write_b16 v188, v81 offset:224
	ds_write_b16_d16_hi v188, v81 offset:256
	v_cvt_pk_bf16_f32 v124, v90, v98
	ds_write_b16 v188, v124 offset:384
	ds_write_b16_d16_hi v188, v124 offset:416
	v_cvt_pk_bf16_f32 v126, v91, v99
	ds_write_b16 v188, v126 offset:544
	ds_write_b16_d16_hi v188, v126 offset:576
	v_mul_f32_e32 v100, v100, v180
	v_mul_f32_e32 v101, v101, v181
	v_mul_f32_e32 v102, v102, v182
	v_mul_f32_e32 v103, v103, v183
	v_mul_f32_e32 v132, v132, v180
	v_mul_f32_e32 v133, v133, v181
	v_mul_f32_e32 v134, v134, v182
	v_mul_f32_e32 v135, v135, v183
	v_mul_f32_e32 v140, v140, v180
	v_mul_f32_e32 v141, v141, v181
	v_mul_f32_e32 v142, v142, v182
	v_mul_f32_e32 v143, v143, v183
	v_mul_f32_e32 v144, v144, v180
	v_mul_f32_e32 v145, v145, v181
	v_mul_f32_e32 v146, v146, v182
	v_mul_f32_e32 v147, v147, v183
	s_waitcnt lgkmcnt(0)
	ds_read_b128 v[164:167], v191 offset:0
	ds_read_b128 v[168:171], v191 offset:64
	s_waitcnt vmcnt(8)
	s_waitcnt lgkmcnt(0)
	v_mfma_f32_16x16x32_bf16 v[100:103], v[164:167], v[44:47], v[100:103]
	v_mfma_f32_16x16x32_bf16 v[132:135], v[164:167], v[48:51], v[132:135]
	v_mfma_f32_16x16x32_bf16 v[140:143], v[164:167], v[52:55], v[140:143]
	v_mfma_f32_16x16x32_bf16 v[144:147], v[164:167], v[56:59], v[144:147]
	v_mfma_f32_16x16x32_bf16 v[100:103], v[168:171], v[60:63], v[100:103]
	v_mfma_f32_16x16x32_bf16 v[132:135], v[168:171], v[64:67], v[132:135]
	v_mfma_f32_16x16x32_bf16 v[140:143], v[168:171], v[68:71], v[140:143]
	v_mfma_f32_16x16x32_bf16 v[144:147], v[168:171], v[72:75], v[144:147]
	s_nop 3
	ds_read_b32 v148, v192 offset:248
	ds_read_b32 v149, v193 offset:248
	ds_read_b32 v150, v194 offset:248
	ds_read_b32 v151, v195 offset:248
	ds_read_b32 v152, v196 offset:248
	ds_read_b32 v153, v197 offset:248
	ds_read_b32 v154, v198 offset:248
	ds_read_b32 v155, v199 offset:248
	ds_read_b32 v156, v192 offset:372
	ds_read_b32 v157, v193 offset:372
	ds_read_b32 v158, v194 offset:372
	ds_read_b32 v159, v195 offset:372
	ds_read_b32 v160, v196 offset:372
	ds_read_b32 v161, v197 offset:372
	ds_read_b32 v162, v198 offset:372
	ds_read_b32 v163, v199 offset:372
	s_add_u32 s8, s6, 2
	s_lshl_b32 s8, s8, 6
	s_add_u32 s8, s8, s7
	s_lshl_b32 s8, s8, 1
	s_add_u32 s24, s18, s8
	s_addc_u32 s25, s19, 0
	global_load_dwordx4 v[44:47], v214, s[24:25]
	global_load_dwordx4 v[48:51], v215, s[24:25]
	global_load_dwordx4 v[52:55], v216, s[24:25]
	global_load_dwordx4 v[56:59], v217, s[24:25]
	s_add_u32 s8, s6, 3
	s_lshl_b32 s8, s8, 6
	s_add_u32 s8, s8, s7
	s_lshl_b32 s8, s8, 1
	s_add_u32 s24, s18, s8
	s_addc_u32 s25, s19, 0
	global_load_dwordx4 v[60:63], v214, s[24:25]
	global_load_dwordx4 v[64:67], v215, s[24:25]
	global_load_dwordx4 v[68:71], v216, s[24:25]
	global_load_dwordx4 v[72:75], v217, s[24:25]
	s_waitcnt vmcnt(8)
	v_mfma_f32_16x16x32_bf16 v[76:79], v[4:7], v[12:15], 0
	v_mfma_f32_16x16x32_bf16 v[76:79], v[8:11], v[16:19], v[76:79]
	v_mfma_f32_16x16x32_bf16 v[84:87], v[4:7], v[20:23], 0
	v_mfma_f32_16x16x32_bf16 v[84:87], v[8:11], v[24:27], v[84:87]
	v_mfma_f32_16x16x32_bf16 v[88:91], v[4:7], v[28:31], 0
	v_mfma_f32_16x16x32_bf16 v[88:91], v[8:11], v[32:35], v[88:91]
	v_mfma_f32_16x16x32_bf16 v[96:99], v[4:7], v[36:39], 0
	v_mfma_f32_16x16x32_bf16 v[96:99], v[8:11], v[40:43], v[96:99]
	s_add_u32 s8, s6, 4
	s_lshl_b32 s8, s8, 6
	s_add_u32 s8, s8, s7
	s_lshl_b32 s8, s8, 13
	s_add_u32 s22, s16, s8
	s_addc_u32 s23, s17, 0
	global_load_dwordx4 v[12:15], v130, s[22:23]
	global_load_dwordx4 v[16:19], v130, s[22:23] offset:64
	s_add_u32 s8, s6, 4
	s_lshl_b32 s8, s8, 6
	s_add_u32 s8, s8, s7
	s_add_u32 s8, s8, 16
	s_lshl_b32 s8, s8, 13
	s_add_u32 s22, s16, s8
	s_addc_u32 s23, s17, 0
	global_load_dwordx4 v[20:23], v130, s[22:23]
	global_load_dwordx4 v[24:27], v130, s[22:23] offset:64
	s_add_u32 s8, s6, 5
	s_lshl_b32 s8, s8, 6
	s_add_u32 s8, s8, s7
	s_lshl_b32 s8, s8, 13
	s_add_u32 s22, s16, s8
	s_addc_u32 s23, s17, 0
	global_load_dwordx4 v[28:31], v130, s[22:23]
	global_load_dwordx4 v[32:35], v130, s[22:23] offset:64
	s_add_u32 s8, s6, 5
	s_lshl_b32 s8, s8, 6
	s_add_u32 s8, s8, s7
	s_add_u32 s8, s8, 16
	s_lshl_b32 s8, s8, 13
	s_add_u32 s22, s16, s8
	s_addc_u32 s23, s17, 0
	global_load_dwordx4 v[36:39], v130, s[22:23]
	global_load_dwordx4 v[40:43], v130, s[22:23] offset:64
	s_nop 7
	s_waitcnt lgkmcnt(0)
	v_add_f32_e32 v148, v148, v200
	v_fma_f32 v76, v76, v218, v148
	v_add_f32_e32 v149, v149, v201
	v_fma_f32 v77, v77, v218, v149
	v_add_f32_e32 v150, v150, v202
	v_fma_f32 v78, v78, v218, v150
	v_add_f32_e32 v151, v151, v203
	v_fma_f32 v79, v79, v218, v151
	v_add_f32_e32 v152, v152, v204
	v_fma_f32 v84, v84, v218, v152
	v_add_f32_e32 v153, v153, v205
	v_fma_f32 v85, v85, v218, v153
	v_add_f32_e32 v154, v154, v206
	v_fma_f32 v86, v86, v218, v154
	v_add_f32_e32 v155, v155, v207
	v_fma_f32 v87, v87, v218, v155
	v_add_f32_e32 v156, v156, v200
	v_fma_f32 v88, v88, v218, v156
	v_add_f32_e32 v157, v157, v201
	v_fma_f32 v89, v89, v218, v157
	v_add_f32_e32 v158, v158, v202
	v_fma_f32 v90, v90, v218, v158
	v_add_f32_e32 v159, v159, v203
	v_fma_f32 v91, v91, v218, v159
	v_add_f32_e32 v160, v160, v204
	v_fma_f32 v96, v96, v218, v160
	v_add_f32_e32 v161, v161, v205
	v_fma_f32 v97, v97, v218, v161
	v_add_f32_e32 v162, v162, v206
	v_fma_f32 v98, v98, v218, v162
	v_add_f32_e32 v163, v163, v207
	v_fma_f32 v99, v99, v218, v163
	v_max3_f32 v184, v76, v84, v88
	v_max_f32_e32 v184, v184, v96
	v_max3_f32 v185, v77, v85, v89
	v_max_f32_e32 v185, v185, v97
	v_max3_f32 v186, v78, v86, v90
	v_max_f32_e32 v186, v186, v98
	v_max3_f32 v187, v79, v87, v91
	v_max_f32_e32 v187, v187, v99
	s_nop 0
	v_max_f32_dpp v184, v184, v184 quad_perm:[1,0,3,2] row_mask:0xf bank_mask:0xf
	v_max_f32_dpp v185, v185, v185 quad_perm:[1,0,3,2] row_mask:0xf bank_mask:0xf
	v_max_f32_dpp v186, v186, v186 quad_perm:[1,0,3,2] row_mask:0xf bank_mask:0xf
	v_max_f32_dpp v187, v187, v187 quad_perm:[1,0,3,2] row_mask:0xf bank_mask:0xf
	v_max_f32_dpp v184, v184, v184 quad_perm:[2,3,0,1] row_mask:0xf bank_mask:0xf
	v_max_f32_dpp v185, v185, v185 quad_perm:[2,3,0,1] row_mask:0xf bank_mask:0xf
	v_max_f32_dpp v186, v186, v186 quad_perm:[2,3,0,1] row_mask:0xf bank_mask:0xf
	v_max_f32_dpp v187, v187, v187 quad_perm:[2,3,0,1] row_mask:0xf bank_mask:0xf
	v_max_f32_dpp v184, v184, v184 row_half_mirror row_mask:0xf bank_mask:0xf
	v_max_f32_dpp v185, v185, v185 row_half_mirror row_mask:0xf bank_mask:0xf
	v_max_f32_dpp v186, v186, v186 row_half_mirror row_mask:0xf bank_mask:0xf
	v_max_f32_dpp v187, v187, v187 row_half_mirror row_mask:0xf bank_mask:0xf
	v_max_f32_dpp v184, v184, v184 row_ror:8 row_mask:0xf bank_mask:0xf
	v_max_f32_dpp v185, v185, v185 row_ror:8 row_mask:0xf bank_mask:0xf
	v_max_f32_dpp v186, v186, v186 row_ror:8 row_mask:0xf bank_mask:0xf
	v_max_f32_dpp v187, v187, v187 row_ror:8 row_mask:0xf bank_mask:0xf
	v_max_f32_e32 v184, v172, v184
	v_max_f32_e32 v185, v173, v185
	v_max_f32_e32 v186, v174, v186
	v_max_f32_e32 v187, v175, v187
	v_sub_f32_e32 v180, v172, v184
	v_mov_b32_e32 v172, v184
	v_sub_f32_e32 v181, v173, v185
	v_mov_b32_e32 v173, v185
	v_sub_f32_e32 v182, v174, v186
	v_mov_b32_e32 v174, v186
	v_sub_f32_e32 v183, v175, v187
	v_mov_b32_e32 v175, v187
	v_mul_f32_e32 v180, 0x3fb8aa3b, v180
	v_mul_f32_e32 v181, 0x3fb8aa3b, v181
	v_mul_f32_e32 v182, 0x3fb8aa3b, v182
	v_mul_f32_e32 v183, 0x3fb8aa3b, v183
	v_exp_f32_e32 v180, v180
	v_exp_f32_e32 v181, v181
	v_exp_f32_e32 v182, v182
	v_exp_f32_e32 v183, v183
	v_mul_f32_e32 v184, 0x3fb8aa3b, v172
	v_mul_f32_e32 v185, 0x3fb8aa3b, v173
	v_mul_f32_e32 v186, 0x3fb8aa3b, v174
	v_mul_f32_e32 v187, 0x3fb8aa3b, v175
	v_fma_f32 v76, v76, v222, -v184
	v_fma_f32 v77, v77, v222, -v185
	v_fma_f32 v78, v78, v222, -v186
	v_fma_f32 v79, v79, v222, -v187
	v_fma_f32 v84, v84, v222, -v184
	v_fma_f32 v85, v85, v222, -v185
	v_fma_f32 v86, v86, v222, -v186
	v_fma_f32 v87, v87, v222, -v187
	v_fma_f32 v88, v88, v222, -v184
	v_fma_f32 v89, v89, v222, -v185
	v_fma_f32 v90, v90, v222, -v186
	v_fma_f32 v91, v91, v222, -v187
	v_fma_f32 v96, v96, v222, -v184
	v_fma_f32 v97, v97, v222, -v185
	v_fma_f32 v98, v98, v222, -v186
	v_fma_f32 v99, v99, v222, -v187
	v_exp_f32_e32 v76, v76
	v_exp_f32_e32 v77, v77
	v_exp_f32_e32 v78, v78
	v_exp_f32_e32 v79, v79
	v_exp_f32_e32 v84, v84
	v_exp_f32_e32 v85, v85
	v_exp_f32_e32 v86, v86
	v_exp_f32_e32 v87, v87
	v_exp_f32_e32 v88, v88
	v_exp_f32_e32 v89, v89
	v_exp_f32_e32 v90, v90
	v_exp_f32_e32 v91, v91
	v_exp_f32_e32 v96, v96
	v_exp_f32_e32 v97, v97
	v_exp_f32_e32 v98, v98
	v_exp_f32_e32 v99, v99
	s_nop 0
	v_mul_f32_e32 v176, v176, v180
	v_mul_f32_e32 v177, v177, v181
	v_mul_f32_e32 v178, v178, v182
	v_mul_f32_e32 v179, v179, v183
	v_add_f32_e32 v176, v176, v76
	v_add_f32_e32 v177, v177, v77
	v_add_f32_e32 v178, v178, v78
	v_add_f32_e32 v179, v179, v79
	v_add_f32_e32 v176, v176, v84
	v_add_f32_e32 v177, v177, v85
	v_add_f32_e32 v178, v178, v86
	v_add_f32_e32 v179, v179, v87
	v_add_f32_e32 v176, v176, v88
	v_add_f32_e32 v177, v177, v89
	v_add_f32_e32 v178, v178, v90
	v_add_f32_e32 v179, v179, v91
	v_add_f32_e32 v176, v176, v96
	v_add_f32_e32 v177, v177, v97
	v_add_f32_e32 v178, v178, v98
	v_add_f32_e32 v179, v179, v99
	v_cvt_pk_bf16_f32 v80, v76, v84
	ds_write_b16 v188, v80 offset:0
	ds_write_b16_d16_hi v188, v80 offset:32
	v_cvt_pk_bf16_f32 v81, v77, v85
	ds_write_b16 v188, v81 offset:160
	ds_write_b16_d16_hi v188, v81 offset:192
	v_cvt_pk_bf16_f32 v124, v78, v86
	ds_write_b16 v188, v124 offset:320
	ds_write_b16_d16_hi v188, v124 offset:352
	v_cvt_pk_bf16_f32 v126, v79, v87
	ds_write_b16 v188, v126 offset:480
	ds_write_b16_d16_hi v188, v126 offset:512
	v_cvt_pk_bf16_f32 v80, v88, v96
	ds_write_b16 v188, v80 offset:64
	ds_write_b16_d16_hi v188, v80 offset:96
	v_cvt_pk_bf16_f32 v81, v89, v97
	ds_write_b16 v188, v81 offset:224
	ds_write_b16_d16_hi v188, v81 offset:256
	v_cvt_pk_bf16_f32 v124, v90, v98
	ds_write_b16 v188, v124 offset:384
	ds_write_b16_d16_hi v188, v124 offset:416
	v_cvt_pk_bf16_f32 v126, v91, v99
	ds_write_b16 v188, v126 offset:544
	ds_write_b16_d16_hi v188, v126 offset:576
	v_mul_f32_e32 v100, v100, v180
	v_mul_f32_e32 v101, v101, v181
	v_mul_f32_e32 v102, v102, v182
	v_mul_f32_e32 v103, v103, v183
	v_mul_f32_e32 v132, v132, v180
	v_mul_f32_e32 v133, v133, v181
	v_mul_f32_e32 v134, v134, v182
	v_mul_f32_e32 v135, v135, v183
	v_mul_f32_e32 v140, v140, v180
	v_mul_f32_e32 v141, v141, v181
	v_mul_f32_e32 v142, v142, v182
	v_mul_f32_e32 v143, v143, v183
	v_mul_f32_e32 v144, v144, v180
	v_mul_f32_e32 v145, v145, v181
	v_mul_f32_e32 v146, v146, v182
	v_mul_f32_e32 v147, v147, v183
	s_waitcnt lgkmcnt(0)
	ds_read_b128 v[164:167], v191 offset:0
	ds_read_b128 v[168:171], v191 offset:64
	s_waitcnt vmcnt(8)
	s_waitcnt lgkmcnt(0)
	v_mfma_f32_16x16x32_bf16 v[100:103], v[164:167], v[44:47], v[100:103]
	v_mfma_f32_16x16x32_bf16 v[132:135], v[164:167], v[48:51], v[132:135]
	v_mfma_f32_16x16x32_bf16 v[140:143], v[164:167], v[52:55], v[140:143]
	v_mfma_f32_16x16x32_bf16 v[144:147], v[164:167], v[56:59], v[144:147]
	v_mfma_f32_16x16x32_bf16 v[100:103], v[168:171], v[60:63], v[100:103]
	v_mfma_f32_16x16x32_bf16 v[132:135], v[168:171], v[64:67], v[132:135]
	v_mfma_f32_16x16x32_bf16 v[140:143], v[168:171], v[68:71], v[140:143]
	v_mfma_f32_16x16x32_bf16 v[144:147], v[168:171], v[72:75], v[144:147]
	s_nop 3
	ds_read_b32 v148, v192 offset:496
	ds_read_b32 v149, v193 offset:496
	ds_read_b32 v150, v194 offset:496
	ds_read_b32 v151, v195 offset:496
	ds_read_b32 v152, v196 offset:496
	ds_read_b32 v153, v197 offset:496
	ds_read_b32 v154, v198 offset:496
	ds_read_b32 v155, v199 offset:496
	ds_read_b32 v156, v192 offset:620
	ds_read_b32 v157, v193 offset:620
	ds_read_b32 v158, v194 offset:620
	ds_read_b32 v159, v195 offset:620
	ds_read_b32 v160, v196 offset:620
	ds_read_b32 v161, v197 offset:620
	ds_read_b32 v162, v198 offset:620
	ds_read_b32 v163, v199 offset:620
	s_add_u32 s8, s6, 4
	s_lshl_b32 s8, s8, 6
	s_add_u32 s8, s8, s7
	s_lshl_b32 s8, s8, 1
	s_add_u32 s24, s18, s8
	s_addc_u32 s25, s19, 0
	global_load_dwordx4 v[44:47], v214, s[24:25]
	global_load_dwordx4 v[48:51], v215, s[24:25]
	global_load_dwordx4 v[52:55], v216, s[24:25]
	global_load_dwordx4 v[56:59], v217, s[24:25]
	s_add_u32 s8, s6, 5
	s_lshl_b32 s8, s8, 6
	s_add_u32 s8, s8, s7
	s_lshl_b32 s8, s8, 1
	s_add_u32 s24, s18, s8
	s_addc_u32 s25, s19, 0
	global_load_dwordx4 v[60:63], v214, s[24:25]
	global_load_dwordx4 v[64:67], v215, s[24:25]
	global_load_dwordx4 v[68:71], v216, s[24:25]
	global_load_dwordx4 v[72:75], v217, s[24:25]
	s_waitcnt vmcnt(8)
	v_mfma_f32_16x16x32_bf16 v[76:79], v[4:7], v[12:15], 0
	v_mfma_f32_16x16x32_bf16 v[76:79], v[8:11], v[16:19], v[76:79]
	v_mfma_f32_16x16x32_bf16 v[84:87], v[4:7], v[20:23], 0
	v_mfma_f32_16x16x32_bf16 v[84:87], v[8:11], v[24:27], v[84:87]
	v_mfma_f32_16x16x32_bf16 v[88:91], v[4:7], v[28:31], 0
	v_mfma_f32_16x16x32_bf16 v[88:91], v[8:11], v[32:35], v[88:91]
	v_mfma_f32_16x16x32_bf16 v[96:99], v[4:7], v[36:39], 0
	v_mfma_f32_16x16x32_bf16 v[96:99], v[8:11], v[40:43], v[96:99]
	s_add_u32 s8, s6, 6
	s_lshl_b32 s8, s8, 6
	s_add_u32 s8, s8, s7
	s_lshl_b32 s8, s8, 13
	s_add_u32 s22, s16, s8
	s_addc_u32 s23, s17, 0
	global_load_dwordx4 v[12:15], v130, s[22:23]
	global_load_dwordx4 v[16:19], v130, s[22:23] offset:64
	s_add_u32 s8, s6, 6
	s_lshl_b32 s8, s8, 6
	s_add_u32 s8, s8, s7
	s_add_u32 s8, s8, 16
	s_lshl_b32 s8, s8, 13
	s_add_u32 s22, s16, s8
	s_addc_u32 s23, s17, 0
	global_load_dwordx4 v[20:23], v130, s[22:23]
	global_load_dwordx4 v[24:27], v130, s[22:23] offset:64
	s_add_u32 s8, s6, 7
	s_lshl_b32 s8, s8, 6
	s_add_u32 s8, s8, s7
	s_lshl_b32 s8, s8, 13
	s_add_u32 s22, s16, s8
	s_addc_u32 s23, s17, 0
	global_load_dwordx4 v[28:31], v130, s[22:23]
	global_load_dwordx4 v[32:35], v130, s[22:23] offset:64
	s_add_u32 s8, s6, 7
	s_lshl_b32 s8, s8, 6
	s_add_u32 s8, s8, s7
	s_add_u32 s8, s8, 16
	s_lshl_b32 s8, s8, 13
	s_add_u32 s22, s16, s8
	s_addc_u32 s23, s17, 0
	global_load_dwordx4 v[36:39], v130, s[22:23]
	global_load_dwordx4 v[40:43], v130, s[22:23] offset:64
	s_nop 7
	s_waitcnt lgkmcnt(0)
	v_add_f32_e32 v148, v148, v200
	v_fma_f32 v76, v76, v218, v148
	v_add_f32_e32 v149, v149, v201
	v_fma_f32 v77, v77, v218, v149
	v_add_f32_e32 v150, v150, v202
	v_fma_f32 v78, v78, v218, v150
	v_add_f32_e32 v151, v151, v203
	v_fma_f32 v79, v79, v218, v151
	v_add_f32_e32 v152, v152, v204
	v_fma_f32 v84, v84, v218, v152
	v_add_f32_e32 v153, v153, v205
	v_fma_f32 v85, v85, v218, v153
	v_add_f32_e32 v154, v154, v206
	v_fma_f32 v86, v86, v218, v154
	v_add_f32_e32 v155, v155, v207
	v_fma_f32 v87, v87, v218, v155
	v_add_f32_e32 v156, v156, v200
	v_fma_f32 v88, v88, v218, v156
	v_add_f32_e32 v157, v157, v201
	v_fma_f32 v89, v89, v218, v157
	v_add_f32_e32 v158, v158, v202
	v_fma_f32 v90, v90, v218, v158
	v_add_f32_e32 v159, v159, v203
	v_fma_f32 v91, v91, v218, v159
	v_add_f32_e32 v160, v160, v204
	v_fma_f32 v96, v96, v218, v160
	v_add_f32_e32 v161, v161, v205
	v_fma_f32 v97, v97, v218, v161
	v_add_f32_e32 v162, v162, v206
	v_fma_f32 v98, v98, v218, v162
	v_add_f32_e32 v163, v163, v207
	v_fma_f32 v99, v99, v218, v163
	v_max3_f32 v184, v76, v84, v88
	v_max_f32_e32 v184, v184, v96
	v_max3_f32 v185, v77, v85, v89
	v_max_f32_e32 v185, v185, v97
	v_max3_f32 v186, v78, v86, v90
	v_max_f32_e32 v186, v186, v98
	v_max3_f32 v187, v79, v87, v91
	v_max_f32_e32 v187, v187, v99
	s_nop 0
	v_max_f32_dpp v184, v184, v184 quad_perm:[1,0,3,2] row_mask:0xf bank_mask:0xf
	v_max_f32_dpp v185, v185, v185 quad_perm:[1,0,3,2] row_mask:0xf bank_mask:0xf
	v_max_f32_dpp v186, v186, v186 quad_perm:[1,0,3,2] row_mask:0xf bank_mask:0xf
	v_max_f32_dpp v187, v187, v187 quad_perm:[1,0,3,2] row_mask:0xf bank_mask:0xf
	v_max_f32_dpp v184, v184, v184 quad_perm:[2,3,0,1] row_mask:0xf bank_mask:0xf
	v_max_f32_dpp v185, v185, v185 quad_perm:[2,3,0,1] row_mask:0xf bank_mask:0xf
	v_max_f32_dpp v186, v186, v186 quad_perm:[2,3,0,1] row_mask:0xf bank_mask:0xf
	v_max_f32_dpp v187, v187, v187 quad_perm:[2,3,0,1] row_mask:0xf bank_mask:0xf
	v_max_f32_dpp v184, v184, v184 row_half_mirror row_mask:0xf bank_mask:0xf
	v_max_f32_dpp v185, v185, v185 row_half_mirror row_mask:0xf bank_mask:0xf
	v_max_f32_dpp v186, v186, v186 row_half_mirror row_mask:0xf bank_mask:0xf
	v_max_f32_dpp v187, v187, v187 row_half_mirror row_mask:0xf bank_mask:0xf
	v_max_f32_dpp v184, v184, v184 row_ror:8 row_mask:0xf bank_mask:0xf
	v_max_f32_dpp v185, v185, v185 row_ror:8 row_mask:0xf bank_mask:0xf
	v_max_f32_dpp v186, v186, v186 row_ror:8 row_mask:0xf bank_mask:0xf
	v_max_f32_dpp v187, v187, v187 row_ror:8 row_mask:0xf bank_mask:0xf
	v_max_f32_e32 v184, v172, v184
	v_max_f32_e32 v185, v173, v185
	v_max_f32_e32 v186, v174, v186
	v_max_f32_e32 v187, v175, v187
	v_sub_f32_e32 v180, v172, v184
	v_mov_b32_e32 v172, v184
	v_sub_f32_e32 v181, v173, v185
	v_mov_b32_e32 v173, v185
	v_sub_f32_e32 v182, v174, v186
	v_mov_b32_e32 v174, v186
	v_sub_f32_e32 v183, v175, v187
	v_mov_b32_e32 v175, v187
	v_mul_f32_e32 v180, 0x3fb8aa3b, v180
	v_mul_f32_e32 v181, 0x3fb8aa3b, v181
	v_mul_f32_e32 v182, 0x3fb8aa3b, v182
	v_mul_f32_e32 v183, 0x3fb8aa3b, v183
	v_exp_f32_e32 v180, v180
	v_exp_f32_e32 v181, v181
	v_exp_f32_e32 v182, v182
	v_exp_f32_e32 v183, v183
	v_mul_f32_e32 v184, 0x3fb8aa3b, v172
	v_mul_f32_e32 v185, 0x3fb8aa3b, v173
	v_mul_f32_e32 v186, 0x3fb8aa3b, v174
	v_mul_f32_e32 v187, 0x3fb8aa3b, v175
	v_fma_f32 v76, v76, v222, -v184
	v_fma_f32 v77, v77, v222, -v185
	v_fma_f32 v78, v78, v222, -v186
	v_fma_f32 v79, v79, v222, -v187
	v_fma_f32 v84, v84, v222, -v184
	v_fma_f32 v85, v85, v222, -v185
	v_fma_f32 v86, v86, v222, -v186
	v_fma_f32 v87, v87, v222, -v187
	v_fma_f32 v88, v88, v222, -v184
	v_fma_f32 v89, v89, v222, -v185
	v_fma_f32 v90, v90, v222, -v186
	v_fma_f32 v91, v91, v222, -v187
	v_fma_f32 v96, v96, v222, -v184
	v_fma_f32 v97, v97, v222, -v185
	v_fma_f32 v98, v98, v222, -v186
	v_fma_f32 v99, v99, v222, -v187
	v_exp_f32_e32 v76, v76
	v_exp_f32_e32 v77, v77
	v_exp_f32_e32 v78, v78
	v_exp_f32_e32 v79, v79
	v_exp_f32_e32 v84, v84
	v_exp_f32_e32 v85, v85
	v_exp_f32_e32 v86, v86
	v_exp_f32_e32 v87, v87
	v_exp_f32_e32 v88, v88
	v_exp_f32_e32 v89, v89
	v_exp_f32_e32 v90, v90
	v_exp_f32_e32 v91, v91
	v_exp_f32_e32 v96, v96
	v_exp_f32_e32 v97, v97
	v_exp_f32_e32 v98, v98
	v_exp_f32_e32 v99, v99
	s_nop 0
	v_mul_f32_e32 v176, v176, v180
	v_mul_f32_e32 v177, v177, v181
	v_mul_f32_e32 v178, v178, v182
	v_mul_f32_e32 v179, v179, v183
	v_add_f32_e32 v176, v176, v76
	v_add_f32_e32 v177, v177, v77
	v_add_f32_e32 v178, v178, v78
	v_add_f32_e32 v179, v179, v79
	v_add_f32_e32 v176, v176, v84
	v_add_f32_e32 v177, v177, v85
	v_add_f32_e32 v178, v178, v86
	v_add_f32_e32 v179, v179, v87
	v_add_f32_e32 v176, v176, v88
	v_add_f32_e32 v177, v177, v89
	v_add_f32_e32 v178, v178, v90
	v_add_f32_e32 v179, v179, v91
	v_add_f32_e32 v176, v176, v96
	v_add_f32_e32 v177, v177, v97
	v_add_f32_e32 v178, v178, v98
	v_add_f32_e32 v179, v179, v99
	v_cvt_pk_bf16_f32 v80, v76, v84
	ds_write_b16 v188, v80 offset:0
	ds_write_b16_d16_hi v188, v80 offset:32
	v_cvt_pk_bf16_f32 v81, v77, v85
	ds_write_b16 v188, v81 offset:160
	ds_write_b16_d16_hi v188, v81 offset:192
	v_cvt_pk_bf16_f32 v124, v78, v86
	ds_write_b16 v188, v124 offset:320
	ds_write_b16_d16_hi v188, v124 offset:352
	v_cvt_pk_bf16_f32 v126, v79, v87
	ds_write_b16 v188, v126 offset:480
	ds_write_b16_d16_hi v188, v126 offset:512
	v_cvt_pk_bf16_f32 v80, v88, v96
	ds_write_b16 v188, v80 offset:64
	ds_write_b16_d16_hi v188, v80 offset:96
	v_cvt_pk_bf16_f32 v81, v89, v97
	ds_write_b16 v188, v81 offset:224
	ds_write_b16_d16_hi v188, v81 offset:256
	v_cvt_pk_bf16_f32 v124, v90, v98
	ds_write_b16 v188, v124 offset:384
	ds_write_b16_d16_hi v188, v124 offset:416
	v_cvt_pk_bf16_f32 v126, v91, v99
	ds_write_b16 v188, v126 offset:544
	ds_write_b16_d16_hi v188, v126 offset:576
	v_mul_f32_e32 v100, v100, v180
	v_mul_f32_e32 v101, v101, v181
	v_mul_f32_e32 v102, v102, v182
	v_mul_f32_e32 v103, v103, v183
	v_mul_f32_e32 v132, v132, v180
	v_mul_f32_e32 v133, v133, v181
	v_mul_f32_e32 v134, v134, v182
	v_mul_f32_e32 v135, v135, v183
	v_mul_f32_e32 v140, v140, v180
	v_mul_f32_e32 v141, v141, v181
	v_mul_f32_e32 v142, v142, v182
	v_mul_f32_e32 v143, v143, v183
	v_mul_f32_e32 v144, v144, v180
	v_mul_f32_e32 v145, v145, v181
	v_mul_f32_e32 v146, v146, v182
	v_mul_f32_e32 v147, v147, v183
	s_waitcnt lgkmcnt(0)
	ds_read_b128 v[164:167], v191 offset:0
	ds_read_b128 v[168:171], v191 offset:64
	s_waitcnt vmcnt(8)
	s_waitcnt lgkmcnt(0)
	v_mfma_f32_16x16x32_bf16 v[100:103], v[164:167], v[44:47], v[100:103]
	v_mfma_f32_16x16x32_bf16 v[132:135], v[164:167], v[48:51], v[132:135]
	v_mfma_f32_16x16x32_bf16 v[140:143], v[164:167], v[52:55], v[140:143]
	v_mfma_f32_16x16x32_bf16 v[144:147], v[164:167], v[56:59], v[144:147]
	v_mfma_f32_16x16x32_bf16 v[100:103], v[168:171], v[60:63], v[100:103]
	v_mfma_f32_16x16x32_bf16 v[132:135], v[168:171], v[64:67], v[132:135]
	v_mfma_f32_16x16x32_bf16 v[140:143], v[168:171], v[68:71], v[140:143]
	v_mfma_f32_16x16x32_bf16 v[144:147], v[168:171], v[72:75], v[144:147]
	s_nop 3
	ds_read_b32 v148, v192 offset:744
	ds_read_b32 v149, v193 offset:744
	ds_read_b32 v150, v194 offset:744
	ds_read_b32 v151, v195 offset:744
	ds_read_b32 v152, v196 offset:744
	ds_read_b32 v153, v197 offset:744
	ds_read_b32 v154, v198 offset:744
	ds_read_b32 v155, v199 offset:744
	ds_read_b32 v156, v192 offset:868
	ds_read_b32 v157, v193 offset:868
	ds_read_b32 v158, v194 offset:868
	ds_read_b32 v159, v195 offset:868
	ds_read_b32 v160, v196 offset:868
	ds_read_b32 v161, v197 offset:868
	ds_read_b32 v162, v198 offset:868
	ds_read_b32 v163, v199 offset:868
	s_add_u32 s8, s6, 6
	s_lshl_b32 s8, s8, 6
	s_add_u32 s8, s8, s7
	s_lshl_b32 s8, s8, 1
	s_add_u32 s24, s18, s8
	s_addc_u32 s25, s19, 0
	global_load_dwordx4 v[44:47], v214, s[24:25]
	global_load_dwordx4 v[48:51], v215, s[24:25]
	global_load_dwordx4 v[52:55], v216, s[24:25]
	global_load_dwordx4 v[56:59], v217, s[24:25]
	s_add_u32 s8, s6, 7
	s_lshl_b32 s8, s8, 6
	s_add_u32 s8, s8, s7
	s_lshl_b32 s8, s8, 1
	s_add_u32 s24, s18, s8
	s_addc_u32 s25, s19, 0
	global_load_dwordx4 v[60:63], v214, s[24:25]
	global_load_dwordx4 v[64:67], v215, s[24:25]
	global_load_dwordx4 v[68:71], v216, s[24:25]
	global_load_dwordx4 v[72:75], v217, s[24:25]
	s_waitcnt vmcnt(8)
	v_mfma_f32_16x16x32_bf16 v[76:79], v[4:7], v[12:15], 0
	v_mfma_f32_16x16x32_bf16 v[76:79], v[8:11], v[16:19], v[76:79]
	v_mfma_f32_16x16x32_bf16 v[84:87], v[4:7], v[20:23], 0
	v_mfma_f32_16x16x32_bf16 v[84:87], v[8:11], v[24:27], v[84:87]
	v_mfma_f32_16x16x32_bf16 v[88:91], v[4:7], v[28:31], 0
	v_mfma_f32_16x16x32_bf16 v[88:91], v[8:11], v[32:35], v[88:91]
	v_mfma_f32_16x16x32_bf16 v[96:99], v[4:7], v[36:39], 0
	v_mfma_f32_16x16x32_bf16 v[96:99], v[8:11], v[40:43], v[96:99]
	ds_read_b128 v[12:15], v136 offset:0
	ds_read_b128 v[16:19], v136 offset:64
	ds_read_b128 v[20:23], v136 offset:2304
	ds_read_b128 v[24:27], v136 offset:2368
	ds_read_b128 v[28:31], v136 offset:4608
	ds_read_b128 v[32:35], v136 offset:4672
	ds_read_b128 v[36:39], v136 offset:6912
	ds_read_b128 v[40:43], v136 offset:6976
	s_nop 7
	s_waitcnt lgkmcnt(8)
	v_add_f32_e32 v148, v148, v200
	v_fma_f32 v76, v76, v218, v148
	v_add_f32_e32 v149, v149, v201
	v_fma_f32 v77, v77, v218, v149
	v_add_f32_e32 v150, v150, v202
	v_fma_f32 v78, v78, v218, v150
	v_add_f32_e32 v151, v151, v203
	v_fma_f32 v79, v79, v218, v151
	v_add_f32_e32 v152, v152, v204
	v_fma_f32 v84, v84, v218, v152
	v_add_f32_e32 v153, v153, v205
	v_fma_f32 v85, v85, v218, v153
	v_add_f32_e32 v154, v154, v206
	v_fma_f32 v86, v86, v218, v154
	v_add_f32_e32 v155, v155, v207
	v_fma_f32 v87, v87, v218, v155
	v_add_f32_e32 v156, v156, v200
	v_fma_f32 v88, v88, v218, v156
	v_add_f32_e32 v157, v157, v201
	v_fma_f32 v89, v89, v218, v157
	v_add_f32_e32 v158, v158, v202
	v_fma_f32 v90, v90, v218, v158
	v_add_f32_e32 v159, v159, v203
	v_fma_f32 v91, v91, v218, v159
	v_add_f32_e32 v160, v160, v204
	v_fma_f32 v96, v96, v218, v160
	v_add_f32_e32 v161, v161, v205
	v_fma_f32 v97, v97, v218, v161
	v_add_f32_e32 v162, v162, v206
	v_fma_f32 v98, v98, v218, v162
	v_add_f32_e32 v163, v163, v207
	v_fma_f32 v99, v99, v218, v163
	v_max3_f32 v184, v76, v84, v88
	v_max_f32_e32 v184, v184, v96
	v_max3_f32 v185, v77, v85, v89
	v_max_f32_e32 v185, v185, v97
	v_max3_f32 v186, v78, v86, v90
	v_max_f32_e32 v186, v186, v98
	v_max3_f32 v187, v79, v87, v91
	v_max_f32_e32 v187, v187, v99
	s_nop 0
	v_max_f32_dpp v184, v184, v184 quad_perm:[1,0,3,2] row_mask:0xf bank_mask:0xf
	v_max_f32_dpp v185, v185, v185 quad_perm:[1,0,3,2] row_mask:0xf bank_mask:0xf
	v_max_f32_dpp v186, v186, v186 quad_perm:[1,0,3,2] row_mask:0xf bank_mask:0xf
	v_max_f32_dpp v187, v187, v187 quad_perm:[1,0,3,2] row_mask:0xf bank_mask:0xf
	v_max_f32_dpp v184, v184, v184 quad_perm:[2,3,0,1] row_mask:0xf bank_mask:0xf
	v_max_f32_dpp v185, v185, v185 quad_perm:[2,3,0,1] row_mask:0xf bank_mask:0xf
	v_max_f32_dpp v186, v186, v186 quad_perm:[2,3,0,1] row_mask:0xf bank_mask:0xf
	v_max_f32_dpp v187, v187, v187 quad_perm:[2,3,0,1] row_mask:0xf bank_mask:0xf
	v_max_f32_dpp v184, v184, v184 row_half_mirror row_mask:0xf bank_mask:0xf
	v_max_f32_dpp v185, v185, v185 row_half_mirror row_mask:0xf bank_mask:0xf
	v_max_f32_dpp v186, v186, v186 row_half_mirror row_mask:0xf bank_mask:0xf
	v_max_f32_dpp v187, v187, v187 row_half_mirror row_mask:0xf bank_mask:0xf
	v_max_f32_dpp v184, v184, v184 row_ror:8 row_mask:0xf bank_mask:0xf
	v_max_f32_dpp v185, v185, v185 row_ror:8 row_mask:0xf bank_mask:0xf
	v_max_f32_dpp v186, v186, v186 row_ror:8 row_mask:0xf bank_mask:0xf
	v_max_f32_dpp v187, v187, v187 row_ror:8 row_mask:0xf bank_mask:0xf
	v_max_f32_e32 v184, v172, v184
	v_max_f32_e32 v185, v173, v185
	v_max_f32_e32 v186, v174, v186
	v_max_f32_e32 v187, v175, v187
	v_sub_f32_e32 v180, v172, v184
	v_mov_b32_e32 v172, v184
	v_sub_f32_e32 v181, v173, v185
	v_mov_b32_e32 v173, v185
	v_sub_f32_e32 v182, v174, v186
	v_mov_b32_e32 v174, v186
	v_sub_f32_e32 v183, v175, v187
	v_mov_b32_e32 v175, v187
	v_mul_f32_e32 v180, 0x3fb8aa3b, v180
	v_mul_f32_e32 v181, 0x3fb8aa3b, v181
	v_mul_f32_e32 v182, 0x3fb8aa3b, v182
	v_mul_f32_e32 v183, 0x3fb8aa3b, v183
	v_exp_f32_e32 v180, v180
	v_exp_f32_e32 v181, v181
	v_exp_f32_e32 v182, v182
	v_exp_f32_e32 v183, v183
	v_mul_f32_e32 v184, 0x3fb8aa3b, v172
	v_mul_f32_e32 v185, 0x3fb8aa3b, v173
	v_mul_f32_e32 v186, 0x3fb8aa3b, v174
	v_mul_f32_e32 v187, 0x3fb8aa3b, v175
	v_fma_f32 v76, v76, v222, -v184
	v_fma_f32 v77, v77, v222, -v185
	v_fma_f32 v78, v78, v222, -v186
	v_fma_f32 v79, v79, v222, -v187
	v_fma_f32 v84, v84, v222, -v184
	v_fma_f32 v85, v85, v222, -v185
	v_fma_f32 v86, v86, v222, -v186
	v_fma_f32 v87, v87, v222, -v187
	v_fma_f32 v88, v88, v222, -v184
	v_fma_f32 v89, v89, v222, -v185
	v_fma_f32 v90, v90, v222, -v186
	v_fma_f32 v91, v91, v222, -v187
	v_fma_f32 v96, v96, v222, -v184
	v_fma_f32 v97, v97, v222, -v185
	v_fma_f32 v98, v98, v222, -v186
	v_fma_f32 v99, v99, v222, -v187
	v_exp_f32_e32 v76, v76
	v_exp_f32_e32 v77, v77
	v_exp_f32_e32 v78, v78
	v_exp_f32_e32 v79, v79
	v_exp_f32_e32 v84, v84
	v_exp_f32_e32 v85, v85
	v_exp_f32_e32 v86, v86
	v_exp_f32_e32 v87, v87
	v_exp_f32_e32 v88, v88
	v_exp_f32_e32 v89, v89
	v_exp_f32_e32 v90, v90
	v_exp_f32_e32 v91, v91
	v_exp_f32_e32 v96, v96
	v_exp_f32_e32 v97, v97
	v_exp_f32_e32 v98, v98
	v_exp_f32_e32 v99, v99
	s_nop 0
	v_mul_f32_e32 v176, v176, v180
	v_mul_f32_e32 v177, v177, v181
	v_mul_f32_e32 v178, v178, v182
	v_mul_f32_e32 v179, v179, v183
	v_add_f32_e32 v176, v176, v76
	v_add_f32_e32 v177, v177, v77
	v_add_f32_e32 v178, v178, v78
	v_add_f32_e32 v179, v179, v79
	v_add_f32_e32 v176, v176, v84
	v_add_f32_e32 v177, v177, v85
	v_add_f32_e32 v178, v178, v86
	v_add_f32_e32 v179, v179, v87
	v_add_f32_e32 v176, v176, v88
	v_add_f32_e32 v177, v177, v89
	v_add_f32_e32 v178, v178, v90
	v_add_f32_e32 v179, v179, v91
	v_add_f32_e32 v176, v176, v96
	v_add_f32_e32 v177, v177, v97
	v_add_f32_e32 v178, v178, v98
	v_add_f32_e32 v179, v179, v99
	v_cvt_pk_bf16_f32 v80, v76, v84
	ds_write_b16 v188, v80 offset:0
	ds_write_b16_d16_hi v188, v80 offset:32
	v_cvt_pk_bf16_f32 v81, v77, v85
	ds_write_b16 v188, v81 offset:160
	ds_write_b16_d16_hi v188, v81 offset:192
	v_cvt_pk_bf16_f32 v124, v78, v86
	ds_write_b16 v188, v124 offset:320
	ds_write_b16_d16_hi v188, v124 offset:352
	v_cvt_pk_bf16_f32 v126, v79, v87
	ds_write_b16 v188, v126 offset:480
	ds_write_b16_d16_hi v188, v126 offset:512
	v_cvt_pk_bf16_f32 v80, v88, v96
	ds_write_b16 v188, v80 offset:64
	ds_write_b16_d16_hi v188, v80 offset:96
	v_cvt_pk_bf16_f32 v81, v89, v97
	ds_write_b16 v188, v81 offset:224
	ds_write_b16_d16_hi v188, v81 offset:256
	v_cvt_pk_bf16_f32 v124, v90, v98
	ds_write_b16 v188, v124 offset:384
	ds_write_b16_d16_hi v188, v124 offset:416
	v_cvt_pk_bf16_f32 v126, v91, v99
	ds_write_b16 v188, v126 offset:544
	ds_write_b16_d16_hi v188, v126 offset:576
	v_mul_f32_e32 v100, v100, v180
	v_mul_f32_e32 v101, v101, v181
	v_mul_f32_e32 v102, v102, v182
	v_mul_f32_e32 v103, v103, v183
	v_mul_f32_e32 v132, v132, v180
	v_mul_f32_e32 v133, v133, v181
	v_mul_f32_e32 v134, v134, v182
	v_mul_f32_e32 v135, v135, v183
	v_mul_f32_e32 v140, v140, v180
	v_mul_f32_e32 v141, v141, v181
	v_mul_f32_e32 v142, v142, v182
	v_mul_f32_e32 v143, v143, v183
	v_mul_f32_e32 v144, v144, v180
	v_mul_f32_e32 v145, v145, v181
	v_mul_f32_e32 v146, v146, v182
	v_mul_f32_e32 v147, v147, v183
	s_waitcnt lgkmcnt(0)
	ds_read_b128 v[164:167], v191 offset:0
	ds_read_b128 v[168:171], v191 offset:64
	s_waitcnt vmcnt(0)
	s_waitcnt lgkmcnt(0)
	v_mfma_f32_16x16x32_bf16 v[100:103], v[164:167], v[44:47], v[100:103]
	v_mfma_f32_16x16x32_bf16 v[132:135], v[164:167], v[48:51], v[132:135]
	v_mfma_f32_16x16x32_bf16 v[140:143], v[164:167], v[52:55], v[140:143]
	v_mfma_f32_16x16x32_bf16 v[144:147], v[164:167], v[56:59], v[144:147]
	v_mfma_f32_16x16x32_bf16 v[100:103], v[168:171], v[60:63], v[100:103]
	v_mfma_f32_16x16x32_bf16 v[132:135], v[168:171], v[64:67], v[132:135]
	v_mfma_f32_16x16x32_bf16 v[140:143], v[168:171], v[68:71], v[140:143]
	v_mfma_f32_16x16x32_bf16 v[144:147], v[168:171], v[72:75], v[144:147]
	s_nop 3
	ds_read_b128 v[44:47], v138 offset:0
	ds_read_b128 v[48:51], v138 offset:8448
	ds_read_b128 v[52:55], v138 offset:16896
	ds_read_b128 v[56:59], v138 offset:25344
	ds_read_b128 v[60:63], v138 offset:64
	ds_read_b128 v[64:67], v138 offset:8512
	ds_read_b128 v[68:71], v138 offset:16960
	ds_read_b128 v[72:75], v138 offset:25408
	s_waitcnt vmcnt(0) lgkmcnt(8)
	v_mfma_f32_16x16x32_bf16 v[76:79], v[4:7], v[12:15], 0
	v_mfma_f32_16x16x32_bf16 v[76:79], v[8:11], v[16:19], v[76:79]
	v_mfma_f32_16x16x32_bf16 v[84:87], v[4:7], v[20:23], 0
	v_mfma_f32_16x16x32_bf16 v[84:87], v[8:11], v[24:27], v[84:87]
	v_mfma_f32_16x16x32_bf16 v[88:91], v[4:7], v[28:31], 0
	v_mfma_f32_16x16x32_bf16 v[88:91], v[8:11], v[32:35], v[88:91]
	v_mfma_f32_16x16x32_bf16 v[96:99], v[4:7], v[36:39], 0
	v_mfma_f32_16x16x32_bf16 v[96:99], v[8:11], v[40:43], v[96:99]
	ds_read_b128 v[12:15], v136 offset:9216
	ds_read_b128 v[16:19], v136 offset:9280
	ds_read_b128 v[20:23], v136 offset:11520
	ds_read_b128 v[24:27], v136 offset:11584
	ds_read_b128 v[28:31], v136 offset:13824
	ds_read_b128 v[32:35], v136 offset:13888
	ds_read_b128 v[36:39], v136 offset:16128
	ds_read_b128 v[40:43], v136 offset:16192
	s_nop 7
	v_mul_f32_e32 v76, 0x3e000000, v76
	v_mul_f32_e32 v77, 0x3e000000, v77
	v_mul_f32_e32 v78, 0x3e000000, v78
	v_mul_f32_e32 v79, 0x3e000000, v79
	v_mul_f32_e32 v84, 0x3e000000, v84
	v_mul_f32_e32 v85, 0x3e000000, v85
	v_mul_f32_e32 v86, 0x3e000000, v86
	v_mul_f32_e32 v87, 0x3e000000, v87
	v_mul_f32_e32 v88, 0x3e000000, v88
	v_mul_f32_e32 v89, 0x3e000000, v89
	v_mul_f32_e32 v90, 0x3e000000, v90
	v_mul_f32_e32 v91, 0x3e000000, v91
	v_mul_f32_e32 v96, 0x3e000000, v96
	v_mul_f32_e32 v97, 0x3e000000, v97
	v_mul_f32_e32 v98, 0x3e000000, v98
	v_mul_f32_e32 v99, 0x3e000000, v99
	v_max3_f32 v184, v76, v84, v88
	v_max_f32_e32 v184, v184, v96
	v_max3_f32 v185, v77, v85, v89
	v_max_f32_e32 v185, v185, v97
	v_max3_f32 v186, v78, v86, v90
	v_max_f32_e32 v186, v186, v98
	v_max3_f32 v187, v79, v87, v91
	v_max_f32_e32 v187, v187, v99
	s_nop 0
	v_max_f32_dpp v184, v184, v184 quad_perm:[1,0,3,2] row_mask:0xf bank_mask:0xf
	v_max_f32_dpp v185, v185, v185 quad_perm:[1,0,3,2] row_mask:0xf bank_mask:0xf
	v_max_f32_dpp v186, v186, v186 quad_perm:[1,0,3,2] row_mask:0xf bank_mask:0xf
	v_max_f32_dpp v187, v187, v187 quad_perm:[1,0,3,2] row_mask:0xf bank_mask:0xf
	v_max_f32_dpp v184, v184, v184 quad_perm:[2,3,0,1] row_mask:0xf bank_mask:0xf
	v_max_f32_dpp v185, v185, v185 quad_perm:[2,3,0,1] row_mask:0xf bank_mask:0xf
	v_max_f32_dpp v186, v186, v186 quad_perm:[2,3,0,1] row_mask:0xf bank_mask:0xf
	v_max_f32_dpp v187, v187, v187 quad_perm:[2,3,0,1] row_mask:0xf bank_mask:0xf
	v_max_f32_dpp v184, v184, v184 row_half_mirror row_mask:0xf bank_mask:0xf
	v_max_f32_dpp v185, v185, v185 row_half_mirror row_mask:0xf bank_mask:0xf
	v_max_f32_dpp v186, v186, v186 row_half_mirror row_mask:0xf bank_mask:0xf
	v_max_f32_dpp v187, v187, v187 row_half_mirror row_mask:0xf bank_mask:0xf
	v_max_f32_dpp v184, v184, v184 row_ror:8 row_mask:0xf bank_mask:0xf
	v_max_f32_dpp v185, v185, v185 row_ror:8 row_mask:0xf bank_mask:0xf
	v_max_f32_dpp v186, v186, v186 row_ror:8 row_mask:0xf bank_mask:0xf
	v_max_f32_dpp v187, v187, v187 row_ror:8 row_mask:0xf bank_mask:0xf
	v_max_f32_e32 v184, v172, v184
	v_max_f32_e32 v185, v173, v185
	v_max_f32_e32 v186, v174, v186
	v_max_f32_e32 v187, v175, v187
	v_sub_f32_e32 v180, v172, v184
	v_mov_b32_e32 v172, v184
	v_sub_f32_e32 v181, v173, v185
	v_mov_b32_e32 v173, v185
	v_sub_f32_e32 v182, v174, v186
	v_mov_b32_e32 v174, v186
	v_sub_f32_e32 v183, v175, v187
	v_mov_b32_e32 v175, v187
	v_mul_f32_e32 v180, 0x3fb8aa3b, v180
	v_mul_f32_e32 v181, 0x3fb8aa3b, v181
	v_mul_f32_e32 v182, 0x3fb8aa3b, v182
	v_mul_f32_e32 v183, 0x3fb8aa3b, v183
	v_exp_f32_e32 v180, v180
	v_exp_f32_e32 v181, v181
	v_exp_f32_e32 v182, v182
	v_exp_f32_e32 v183, v183
	v_mul_f32_e32 v184, 0x3fb8aa3b, v172
	v_mul_f32_e32 v185, 0x3fb8aa3b, v173
	v_mul_f32_e32 v186, 0x3fb8aa3b, v174
	v_mul_f32_e32 v187, 0x3fb8aa3b, v175
	v_fma_f32 v76, v76, v222, -v184
	v_fma_f32 v77, v77, v222, -v185
	v_fma_f32 v78, v78, v222, -v186
	v_fma_f32 v79, v79, v222, -v187
	v_fma_f32 v84, v84, v222, -v184
	v_fma_f32 v85, v85, v222, -v185
	v_fma_f32 v86, v86, v222, -v186
	v_fma_f32 v87, v87, v222, -v187
	v_fma_f32 v88, v88, v222, -v184
	v_fma_f32 v89, v89, v222, -v185
	v_fma_f32 v90, v90, v222, -v186
	v_fma_f32 v91, v91, v222, -v187
	v_fma_f32 v96, v96, v222, -v184
	v_fma_f32 v97, v97, v222, -v185
	v_fma_f32 v98, v98, v222, -v186
	v_fma_f32 v99, v99, v222, -v187
	v_exp_f32_e32 v76, v76
	v_exp_f32_e32 v77, v77
	v_exp_f32_e32 v78, v78
	v_exp_f32_e32 v79, v79
	v_exp_f32_e32 v84, v84
	v_exp_f32_e32 v85, v85
	v_exp_f32_e32 v86, v86
	v_exp_f32_e32 v87, v87
	v_exp_f32_e32 v88, v88
	v_exp_f32_e32 v89, v89
	v_exp_f32_e32 v90, v90
	v_exp_f32_e32 v91, v91
	v_exp_f32_e32 v96, v96
	v_exp_f32_e32 v97, v97
	v_exp_f32_e32 v98, v98
	v_exp_f32_e32 v99, v99
	s_nop 0
	v_mul_f32_e32 v176, v176, v180
	v_mul_f32_e32 v177, v177, v181
	v_mul_f32_e32 v178, v178, v182
	v_mul_f32_e32 v179, v179, v183
	v_add_f32_e32 v176, v176, v76
	v_add_f32_e32 v177, v177, v77
	v_add_f32_e32 v178, v178, v78
	v_add_f32_e32 v179, v179, v79
	v_add_f32_e32 v176, v176, v84
	v_add_f32_e32 v177, v177, v85
	v_add_f32_e32 v178, v178, v86
	v_add_f32_e32 v179, v179, v87
	v_add_f32_e32 v176, v176, v88
	v_add_f32_e32 v177, v177, v89
	v_add_f32_e32 v178, v178, v90
	v_add_f32_e32 v179, v179, v91
	v_add_f32_e32 v176, v176, v96
	v_add_f32_e32 v177, v177, v97
	v_add_f32_e32 v178, v178, v98
	v_add_f32_e32 v179, v179, v99
	v_cvt_pk_bf16_f32 v80, v76, v84
	ds_write_b16 v188, v80 offset:0
	ds_write_b16_d16_hi v188, v80 offset:32
	v_cvt_pk_bf16_f32 v81, v77, v85
	ds_write_b16 v188, v81 offset:160
	ds_write_b16_d16_hi v188, v81 offset:192
	v_cvt_pk_bf16_f32 v124, v78, v86
	ds_write_b16 v188, v124 offset:320
	ds_write_b16_d16_hi v188, v124 offset:352
	v_cvt_pk_bf16_f32 v126, v79, v87
	ds_write_b16 v188, v126 offset:480
	ds_write_b16_d16_hi v188, v126 offset:512
	v_cvt_pk_bf16_f32 v80, v88, v96
	ds_write_b16 v188, v80 offset:64
	ds_write_b16_d16_hi v188, v80 offset:96
	v_cvt_pk_bf16_f32 v81, v89, v97
	ds_write_b16 v188, v81 offset:224
	ds_write_b16_d16_hi v188, v81 offset:256
	v_cvt_pk_bf16_f32 v124, v90, v98
	ds_write_b16 v188, v124 offset:384
	ds_write_b16_d16_hi v188, v124 offset:416
	v_cvt_pk_bf16_f32 v126, v91, v99
	ds_write_b16 v188, v126 offset:544
	ds_write_b16_d16_hi v188, v126 offset:576
	v_mul_f32_e32 v100, v100, v180
	v_mul_f32_e32 v101, v101, v181
	v_mul_f32_e32 v102, v102, v182
	v_mul_f32_e32 v103, v103, v183
	v_mul_f32_e32 v132, v132, v180
	v_mul_f32_e32 v133, v133, v181
	v_mul_f32_e32 v134, v134, v182
	v_mul_f32_e32 v135, v135, v183
	v_mul_f32_e32 v140, v140, v180
	v_mul_f32_e32 v141, v141, v181
	v_mul_f32_e32 v142, v142, v182
	v_mul_f32_e32 v143, v143, v183
	v_mul_f32_e32 v144, v144, v180
	v_mul_f32_e32 v145, v145, v181
	v_mul_f32_e32 v146, v146, v182
	v_mul_f32_e32 v147, v147, v183
	s_waitcnt lgkmcnt(0)
	ds_read_b128 v[164:167], v191 offset:0
	ds_read_b128 v[168:171], v191 offset:64
	s_waitcnt lgkmcnt(0)
	v_mfma_f32_16x16x32_bf16 v[100:103], v[164:167], v[44:47], v[100:103]
	v_mfma_f32_16x16x32_bf16 v[132:135], v[164:167], v[48:51], v[132:135]
	v_mfma_f32_16x16x32_bf16 v[140:143], v[164:167], v[52:55], v[140:143]
	v_mfma_f32_16x16x32_bf16 v[144:147], v[164:167], v[56:59], v[144:147]
	v_mfma_f32_16x16x32_bf16 v[100:103], v[168:171], v[60:63], v[100:103]
	v_mfma_f32_16x16x32_bf16 v[132:135], v[168:171], v[64:67], v[132:135]
	v_mfma_f32_16x16x32_bf16 v[140:143], v[168:171], v[68:71], v[140:143]
	v_mfma_f32_16x16x32_bf16 v[144:147], v[168:171], v[72:75], v[144:147]
	s_nop 3
	ds_read_b128 v[44:47], v138 offset:128
	ds_read_b128 v[48:51], v138 offset:8576
	ds_read_b128 v[52:55], v138 offset:17024
	ds_read_b128 v[56:59], v138 offset:25472
	ds_read_b128 v[60:63], v138 offset:192
	ds_read_b128 v[64:67], v138 offset:8640
	ds_read_b128 v[68:71], v138 offset:17088
	ds_read_b128 v[72:75], v138 offset:25536
	s_waitcnt lgkmcnt(8)
	v_mfma_f32_16x16x32_bf16 v[76:79], v[4:7], v[12:15], 0
	v_mfma_f32_16x16x32_bf16 v[76:79], v[8:11], v[16:19], v[76:79]
	v_mfma_f32_16x16x32_bf16 v[84:87], v[4:7], v[20:23], 0
	v_mfma_f32_16x16x32_bf16 v[84:87], v[8:11], v[24:27], v[84:87]
	v_mfma_f32_16x16x32_bf16 v[88:91], v[4:7], v[28:31], 0
	v_mfma_f32_16x16x32_bf16 v[88:91], v[8:11], v[32:35], v[88:91]
	v_mfma_f32_16x16x32_bf16 v[96:99], v[4:7], v[36:39], 0
	v_mfma_f32_16x16x32_bf16 v[96:99], v[8:11], v[40:43], v[96:99]
	ds_read_b128 v[12:15], v136 offset:18432
	ds_read_b128 v[16:19], v136 offset:18496
	ds_read_b128 v[20:23], v136 offset:20736
	ds_read_b128 v[24:27], v136 offset:20800
	ds_read_b128 v[28:31], v136 offset:23040
	ds_read_b128 v[32:35], v136 offset:23104
	ds_read_b128 v[36:39], v136 offset:25344
	ds_read_b128 v[40:43], v136 offset:25408
	s_nop 7
	v_mul_f32_e32 v76, 0x3e000000, v76
	v_mul_f32_e32 v77, 0x3e000000, v77
	v_mul_f32_e32 v78, 0x3e000000, v78
	v_mul_f32_e32 v79, 0x3e000000, v79
	v_mul_f32_e32 v84, 0x3e000000, v84
	v_mul_f32_e32 v85, 0x3e000000, v85
	v_mul_f32_e32 v86, 0x3e000000, v86
	v_mul_f32_e32 v87, 0x3e000000, v87
	v_mul_f32_e32 v88, 0x3e000000, v88
	v_mul_f32_e32 v89, 0x3e000000, v89
	v_mul_f32_e32 v90, 0x3e000000, v90
	v_mul_f32_e32 v91, 0x3e000000, v91
	v_mul_f32_e32 v96, 0x3e000000, v96
	v_mul_f32_e32 v97, 0x3e000000, v97
	v_mul_f32_e32 v98, 0x3e000000, v98
	v_mul_f32_e32 v99, 0x3e000000, v99
	v_max3_f32 v184, v76, v84, v88
	v_max_f32_e32 v184, v184, v96
	v_max3_f32 v185, v77, v85, v89
	v_max_f32_e32 v185, v185, v97
	v_max3_f32 v186, v78, v86, v90
	v_max_f32_e32 v186, v186, v98
	v_max3_f32 v187, v79, v87, v91
	v_max_f32_e32 v187, v187, v99
	s_nop 0
	v_max_f32_dpp v184, v184, v184 quad_perm:[1,0,3,2] row_mask:0xf bank_mask:0xf
	v_max_f32_dpp v185, v185, v185 quad_perm:[1,0,3,2] row_mask:0xf bank_mask:0xf
	v_max_f32_dpp v186, v186, v186 quad_perm:[1,0,3,2] row_mask:0xf bank_mask:0xf
	v_max_f32_dpp v187, v187, v187 quad_perm:[1,0,3,2] row_mask:0xf bank_mask:0xf
	v_max_f32_dpp v184, v184, v184 quad_perm:[2,3,0,1] row_mask:0xf bank_mask:0xf
	v_max_f32_dpp v185, v185, v185 quad_perm:[2,3,0,1] row_mask:0xf bank_mask:0xf
	v_max_f32_dpp v186, v186, v186 quad_perm:[2,3,0,1] row_mask:0xf bank_mask:0xf
	v_max_f32_dpp v187, v187, v187 quad_perm:[2,3,0,1] row_mask:0xf bank_mask:0xf
	v_max_f32_dpp v184, v184, v184 row_half_mirror row_mask:0xf bank_mask:0xf
	v_max_f32_dpp v185, v185, v185 row_half_mirror row_mask:0xf bank_mask:0xf
	v_max_f32_dpp v186, v186, v186 row_half_mirror row_mask:0xf bank_mask:0xf
	v_max_f32_dpp v187, v187, v187 row_half_mirror row_mask:0xf bank_mask:0xf
	v_max_f32_dpp v184, v184, v184 row_ror:8 row_mask:0xf bank_mask:0xf
	v_max_f32_dpp v185, v185, v185 row_ror:8 row_mask:0xf bank_mask:0xf
	v_max_f32_dpp v186, v186, v186 row_ror:8 row_mask:0xf bank_mask:0xf
	v_max_f32_dpp v187, v187, v187 row_ror:8 row_mask:0xf bank_mask:0xf
	v_max_f32_e32 v184, v172, v184
	v_max_f32_e32 v185, v173, v185
	v_max_f32_e32 v186, v174, v186
	v_max_f32_e32 v187, v175, v187
	v_sub_f32_e32 v180, v172, v184
	v_mov_b32_e32 v172, v184
	v_sub_f32_e32 v181, v173, v185
	v_mov_b32_e32 v173, v185
	v_sub_f32_e32 v182, v174, v186
	v_mov_b32_e32 v174, v186
	v_sub_f32_e32 v183, v175, v187
	v_mov_b32_e32 v175, v187
	v_mul_f32_e32 v180, 0x3fb8aa3b, v180
	v_mul_f32_e32 v181, 0x3fb8aa3b, v181
	v_mul_f32_e32 v182, 0x3fb8aa3b, v182
	v_mul_f32_e32 v183, 0x3fb8aa3b, v183
	v_exp_f32_e32 v180, v180
	v_exp_f32_e32 v181, v181
	v_exp_f32_e32 v182, v182
	v_exp_f32_e32 v183, v183
	v_mul_f32_e32 v184, 0x3fb8aa3b, v172
	v_mul_f32_e32 v185, 0x3fb8aa3b, v173
	v_mul_f32_e32 v186, 0x3fb8aa3b, v174
	v_mul_f32_e32 v187, 0x3fb8aa3b, v175
	v_fma_f32 v76, v76, v222, -v184
	v_fma_f32 v77, v77, v222, -v185
	v_fma_f32 v78, v78, v222, -v186
	v_fma_f32 v79, v79, v222, -v187
	v_fma_f32 v84, v84, v222, -v184
	v_fma_f32 v85, v85, v222, -v185
	v_fma_f32 v86, v86, v222, -v186
	v_fma_f32 v87, v87, v222, -v187
	v_fma_f32 v88, v88, v222, -v184
	v_fma_f32 v89, v89, v222, -v185
	v_fma_f32 v90, v90, v222, -v186
	v_fma_f32 v91, v91, v222, -v187
	v_fma_f32 v96, v96, v222, -v184
	v_fma_f32 v97, v97, v222, -v185
	v_fma_f32 v98, v98, v222, -v186
	v_fma_f32 v99, v99, v222, -v187
	v_exp_f32_e32 v76, v76
	v_exp_f32_e32 v77, v77
	v_exp_f32_e32 v78, v78
	v_exp_f32_e32 v79, v79
	v_exp_f32_e32 v84, v84
	v_exp_f32_e32 v85, v85
	v_exp_f32_e32 v86, v86
	v_exp_f32_e32 v87, v87
	v_exp_f32_e32 v88, v88
	v_exp_f32_e32 v89, v89
	v_exp_f32_e32 v90, v90
	v_exp_f32_e32 v91, v91
	v_exp_f32_e32 v96, v96
	v_exp_f32_e32 v97, v97
	v_exp_f32_e32 v98, v98
	v_exp_f32_e32 v99, v99
	s_nop 0
	v_mul_f32_e32 v176, v176, v180
	v_mul_f32_e32 v177, v177, v181
	v_mul_f32_e32 v178, v178, v182
	v_mul_f32_e32 v179, v179, v183
	v_add_f32_e32 v176, v176, v76
	v_add_f32_e32 v177, v177, v77
	v_add_f32_e32 v178, v178, v78
	v_add_f32_e32 v179, v179, v79
	v_add_f32_e32 v176, v176, v84
	v_add_f32_e32 v177, v177, v85
	v_add_f32_e32 v178, v178, v86
	v_add_f32_e32 v179, v179, v87
	v_add_f32_e32 v176, v176, v88
	v_add_f32_e32 v177, v177, v89
	v_add_f32_e32 v178, v178, v90
	v_add_f32_e32 v179, v179, v91
	v_add_f32_e32 v176, v176, v96
	v_add_f32_e32 v177, v177, v97
	v_add_f32_e32 v178, v178, v98
	v_add_f32_e32 v179, v179, v99
	v_cvt_pk_bf16_f32 v80, v76, v84
	ds_write_b16 v188, v80 offset:0
	ds_write_b16_d16_hi v188, v80 offset:32
	v_cvt_pk_bf16_f32 v81, v77, v85
	ds_write_b16 v188, v81 offset:160
	ds_write_b16_d16_hi v188, v81 offset:192
	v_cvt_pk_bf16_f32 v124, v78, v86
	ds_write_b16 v188, v124 offset:320
	ds_write_b16_d16_hi v188, v124 offset:352
	v_cvt_pk_bf16_f32 v126, v79, v87
	ds_write_b16 v188, v126 offset:480
	ds_write_b16_d16_hi v188, v126 offset:512
	v_cvt_pk_bf16_f32 v80, v88, v96
	ds_write_b16 v188, v80 offset:64
	ds_write_b16_d16_hi v188, v80 offset:96
	v_cvt_pk_bf16_f32 v81, v89, v97
	ds_write_b16 v188, v81 offset:224
	ds_write_b16_d16_hi v188, v81 offset:256
	v_cvt_pk_bf16_f32 v124, v90, v98
	ds_write_b16 v188, v124 offset:384
	ds_write_b16_d16_hi v188, v124 offset:416
	v_cvt_pk_bf16_f32 v126, v91, v99
	ds_write_b16 v188, v126 offset:544
	ds_write_b16_d16_hi v188, v126 offset:576
	v_mul_f32_e32 v100, v100, v180
	v_mul_f32_e32 v101, v101, v181
	v_mul_f32_e32 v102, v102, v182
	v_mul_f32_e32 v103, v103, v183
	v_mul_f32_e32 v132, v132, v180
	v_mul_f32_e32 v133, v133, v181
	v_mul_f32_e32 v134, v134, v182
	v_mul_f32_e32 v135, v135, v183
	v_mul_f32_e32 v140, v140, v180
	v_mul_f32_e32 v141, v141, v181
	v_mul_f32_e32 v142, v142, v182
	v_mul_f32_e32 v143, v143, v183
	v_mul_f32_e32 v144, v144, v180
	v_mul_f32_e32 v145, v145, v181
	v_mul_f32_e32 v146, v146, v182
	v_mul_f32_e32 v147, v147, v183
	s_waitcnt lgkmcnt(0)
	ds_read_b128 v[164:167], v191 offset:0
	ds_read_b128 v[168:171], v191 offset:64
	s_waitcnt lgkmcnt(0)
	v_mfma_f32_16x16x32_bf16 v[100:103], v[164:167], v[44:47], v[100:103]
	v_mfma_f32_16x16x32_bf16 v[132:135], v[164:167], v[48:51], v[132:135]
	v_mfma_f32_16x16x32_bf16 v[140:143], v[164:167], v[52:55], v[140:143]
	v_mfma_f32_16x16x32_bf16 v[144:147], v[164:167], v[56:59], v[144:147]
	v_mfma_f32_16x16x32_bf16 v[100:103], v[168:171], v[60:63], v[100:103]
	v_mfma_f32_16x16x32_bf16 v[132:135], v[168:171], v[64:67], v[132:135]
	v_mfma_f32_16x16x32_bf16 v[140:143], v[168:171], v[68:71], v[140:143]
	v_mfma_f32_16x16x32_bf16 v[144:147], v[168:171], v[72:75], v[144:147]
	s_nop 3
	ds_read_b128 v[44:47], v138 offset:256
	ds_read_b128 v[48:51], v138 offset:8704
	ds_read_b128 v[52:55], v138 offset:17152
	ds_read_b128 v[56:59], v138 offset:25600
	ds_read_b128 v[60:63], v138 offset:320
	ds_read_b128 v[64:67], v138 offset:8768
	ds_read_b128 v[68:71], v138 offset:17216
	ds_read_b128 v[72:75], v138 offset:25664
	s_waitcnt lgkmcnt(8)
	v_mfma_f32_16x16x32_bf16 v[76:79], v[4:7], v[12:15], 0
	v_mfma_f32_16x16x32_bf16 v[76:79], v[8:11], v[16:19], v[76:79]
	v_mfma_f32_16x16x32_bf16 v[84:87], v[4:7], v[20:23], 0
	v_mfma_f32_16x16x32_bf16 v[84:87], v[8:11], v[24:27], v[84:87]
	v_mfma_f32_16x16x32_bf16 v[88:91], v[4:7], v[28:31], 0
	v_mfma_f32_16x16x32_bf16 v[88:91], v[8:11], v[32:35], v[88:91]
	v_mfma_f32_16x16x32_bf16 v[96:99], v[4:7], v[36:39], 0
	v_mfma_f32_16x16x32_bf16 v[96:99], v[8:11], v[40:43], v[96:99]
	ds_read_b128 v[12:15], v136 offset:27648
	ds_read_b128 v[16:19], v136 offset:27712
	ds_read_b128 v[20:23], v136 offset:29952
	ds_read_b128 v[24:27], v136 offset:30016
	ds_read_b128 v[28:31], v136 offset:32256
	ds_read_b128 v[32:35], v136 offset:32320
	ds_read_b128 v[36:39], v136 offset:34560
	ds_read_b128 v[40:43], v136 offset:34624
	s_nop 7
	v_mul_f32_e32 v76, 0x3e000000, v76
	v_mul_f32_e32 v77, 0x3e000000, v77
	v_mul_f32_e32 v78, 0x3e000000, v78
	v_mul_f32_e32 v79, 0x3e000000, v79
	v_mul_f32_e32 v84, 0x3e000000, v84
	v_mul_f32_e32 v85, 0x3e000000, v85
	v_mul_f32_e32 v86, 0x3e000000, v86
	v_mul_f32_e32 v87, 0x3e000000, v87
	v_mul_f32_e32 v88, 0x3e000000, v88
	v_mul_f32_e32 v89, 0x3e000000, v89
	v_mul_f32_e32 v90, 0x3e000000, v90
	v_mul_f32_e32 v91, 0x3e000000, v91
	v_mul_f32_e32 v96, 0x3e000000, v96
	v_mul_f32_e32 v97, 0x3e000000, v97
	v_mul_f32_e32 v98, 0x3e000000, v98
	v_mul_f32_e32 v99, 0x3e000000, v99
	v_max3_f32 v184, v76, v84, v88
	v_max_f32_e32 v184, v184, v96
	v_max3_f32 v185, v77, v85, v89
	v_max_f32_e32 v185, v185, v97
	v_max3_f32 v186, v78, v86, v90
	v_max_f32_e32 v186, v186, v98
	v_max3_f32 v187, v79, v87, v91
	v_max_f32_e32 v187, v187, v99
	s_nop 0
	v_max_f32_dpp v184, v184, v184 quad_perm:[1,0,3,2] row_mask:0xf bank_mask:0xf
	v_max_f32_dpp v185, v185, v185 quad_perm:[1,0,3,2] row_mask:0xf bank_mask:0xf
	v_max_f32_dpp v186, v186, v186 quad_perm:[1,0,3,2] row_mask:0xf bank_mask:0xf
	v_max_f32_dpp v187, v187, v187 quad_perm:[1,0,3,2] row_mask:0xf bank_mask:0xf
	v_max_f32_dpp v184, v184, v184 quad_perm:[2,3,0,1] row_mask:0xf bank_mask:0xf
	v_max_f32_dpp v185, v185, v185 quad_perm:[2,3,0,1] row_mask:0xf bank_mask:0xf
	v_max_f32_dpp v186, v186, v186 quad_perm:[2,3,0,1] row_mask:0xf bank_mask:0xf
	v_max_f32_dpp v187, v187, v187 quad_perm:[2,3,0,1] row_mask:0xf bank_mask:0xf
	v_max_f32_dpp v184, v184, v184 row_half_mirror row_mask:0xf bank_mask:0xf
	v_max_f32_dpp v185, v185, v185 row_half_mirror row_mask:0xf bank_mask:0xf
	v_max_f32_dpp v186, v186, v186 row_half_mirror row_mask:0xf bank_mask:0xf
	v_max_f32_dpp v187, v187, v187 row_half_mirror row_mask:0xf bank_mask:0xf
	v_max_f32_dpp v184, v184, v184 row_ror:8 row_mask:0xf bank_mask:0xf
	v_max_f32_dpp v185, v185, v185 row_ror:8 row_mask:0xf bank_mask:0xf
	v_max_f32_dpp v186, v186, v186 row_ror:8 row_mask:0xf bank_mask:0xf
	v_max_f32_dpp v187, v187, v187 row_ror:8 row_mask:0xf bank_mask:0xf
	v_max_f32_e32 v184, v172, v184
	v_max_f32_e32 v185, v173, v185
	v_max_f32_e32 v186, v174, v186
	v_max_f32_e32 v187, v175, v187
	v_sub_f32_e32 v180, v172, v184
	v_mov_b32_e32 v172, v184
	v_sub_f32_e32 v181, v173, v185
	v_mov_b32_e32 v173, v185
	v_sub_f32_e32 v182, v174, v186
	v_mov_b32_e32 v174, v186
	v_sub_f32_e32 v183, v175, v187
	v_mov_b32_e32 v175, v187
	v_mul_f32_e32 v180, 0x3fb8aa3b, v180
	v_mul_f32_e32 v181, 0x3fb8aa3b, v181
	v_mul_f32_e32 v182, 0x3fb8aa3b, v182
	v_mul_f32_e32 v183, 0x3fb8aa3b, v183
	v_exp_f32_e32 v180, v180
	v_exp_f32_e32 v181, v181
	v_exp_f32_e32 v182, v182
	v_exp_f32_e32 v183, v183
	v_mul_f32_e32 v184, 0x3fb8aa3b, v172
	v_mul_f32_e32 v185, 0x3fb8aa3b, v173
	v_mul_f32_e32 v186, 0x3fb8aa3b, v174
	v_mul_f32_e32 v187, 0x3fb8aa3b, v175
	v_fma_f32 v76, v76, v222, -v184
	v_fma_f32 v77, v77, v222, -v185
	v_fma_f32 v78, v78, v222, -v186
	v_fma_f32 v79, v79, v222, -v187
	v_fma_f32 v84, v84, v222, -v184
	v_fma_f32 v85, v85, v222, -v185
	v_fma_f32 v86, v86, v222, -v186
	v_fma_f32 v87, v87, v222, -v187
	v_fma_f32 v88, v88, v222, -v184
	v_fma_f32 v89, v89, v222, -v185
	v_fma_f32 v90, v90, v222, -v186
	v_fma_f32 v91, v91, v222, -v187
	v_fma_f32 v96, v96, v222, -v184
	v_fma_f32 v97, v97, v222, -v185
	v_fma_f32 v98, v98, v222, -v186
	v_fma_f32 v99, v99, v222, -v187
	v_exp_f32_e32 v76, v76
	v_exp_f32_e32 v77, v77
	v_exp_f32_e32 v78, v78
	v_exp_f32_e32 v79, v79
	v_exp_f32_e32 v84, v84
	v_exp_f32_e32 v85, v85
	v_exp_f32_e32 v86, v86
	v_exp_f32_e32 v87, v87
	v_exp_f32_e32 v88, v88
	v_exp_f32_e32 v89, v89
	v_exp_f32_e32 v90, v90
	v_exp_f32_e32 v91, v91
	v_exp_f32_e32 v96, v96
	v_exp_f32_e32 v97, v97
	v_exp_f32_e32 v98, v98
	v_exp_f32_e32 v99, v99
	s_nop 0
	v_mul_f32_e32 v176, v176, v180
	v_mul_f32_e32 v177, v177, v181
	v_mul_f32_e32 v178, v178, v182
	v_mul_f32_e32 v179, v179, v183
	v_add_f32_e32 v176, v176, v76
	v_add_f32_e32 v177, v177, v77
	v_add_f32_e32 v178, v178, v78
	v_add_f32_e32 v179, v179, v79
	v_add_f32_e32 v176, v176, v84
	v_add_f32_e32 v177, v177, v85
	v_add_f32_e32 v178, v178, v86
	v_add_f32_e32 v179, v179, v87
	v_add_f32_e32 v176, v176, v88
	v_add_f32_e32 v177, v177, v89
	v_add_f32_e32 v178, v178, v90
	v_add_f32_e32 v179, v179, v91
	v_add_f32_e32 v176, v176, v96
	v_add_f32_e32 v177, v177, v97
	v_add_f32_e32 v178, v178, v98
	v_add_f32_e32 v179, v179, v99
	v_cvt_pk_bf16_f32 v80, v76, v84
	ds_write_b16 v188, v80 offset:0
	ds_write_b16_d16_hi v188, v80 offset:32
	v_cvt_pk_bf16_f32 v81, v77, v85
	ds_write_b16 v188, v81 offset:160
	ds_write_b16_d16_hi v188, v81 offset:192
	v_cvt_pk_bf16_f32 v124, v78, v86
	ds_write_b16 v188, v124 offset:320
	ds_write_b16_d16_hi v188, v124 offset:352
	v_cvt_pk_bf16_f32 v126, v79, v87
	ds_write_b16 v188, v126 offset:480
	ds_write_b16_d16_hi v188, v126 offset:512
	v_cvt_pk_bf16_f32 v80, v88, v96
	ds_write_b16 v188, v80 offset:64
	ds_write_b16_d16_hi v188, v80 offset:96
	v_cvt_pk_bf16_f32 v81, v89, v97
	ds_write_b16 v188, v81 offset:224
	ds_write_b16_d16_hi v188, v81 offset:256
	v_cvt_pk_bf16_f32 v124, v90, v98
	ds_write_b16 v188, v124 offset:384
	ds_write_b16_d16_hi v188, v124 offset:416
	v_cvt_pk_bf16_f32 v126, v91, v99
	ds_write_b16 v188, v126 offset:544
	ds_write_b16_d16_hi v188, v126 offset:576
	v_mul_f32_e32 v100, v100, v180
	v_mul_f32_e32 v101, v101, v181
	v_mul_f32_e32 v102, v102, v182
	v_mul_f32_e32 v103, v103, v183
	v_mul_f32_e32 v132, v132, v180
	v_mul_f32_e32 v133, v133, v181
	v_mul_f32_e32 v134, v134, v182
	v_mul_f32_e32 v135, v135, v183
	v_mul_f32_e32 v140, v140, v180
	v_mul_f32_e32 v141, v141, v181
	v_mul_f32_e32 v142, v142, v182
	v_mul_f32_e32 v143, v143, v183
	v_mul_f32_e32 v144, v144, v180
	v_mul_f32_e32 v145, v145, v181
	v_mul_f32_e32 v146, v146, v182
	v_mul_f32_e32 v147, v147, v183
	s_waitcnt lgkmcnt(0)
	ds_read_b128 v[164:167], v191 offset:0
	ds_read_b128 v[168:171], v191 offset:64
	s_waitcnt lgkmcnt(0)
	v_mfma_f32_16x16x32_bf16 v[100:103], v[164:167], v[44:47], v[100:103]
	v_mfma_f32_16x16x32_bf16 v[132:135], v[164:167], v[48:51], v[132:135]
	v_mfma_f32_16x16x32_bf16 v[140:143], v[164:167], v[52:55], v[140:143]
	v_mfma_f32_16x16x32_bf16 v[144:147], v[164:167], v[56:59], v[144:147]
	v_mfma_f32_16x16x32_bf16 v[100:103], v[168:171], v[60:63], v[100:103]
	v_mfma_f32_16x16x32_bf16 v[132:135], v[168:171], v[64:67], v[132:135]
	v_mfma_f32_16x16x32_bf16 v[140:143], v[168:171], v[68:71], v[140:143]
	v_mfma_f32_16x16x32_bf16 v[144:147], v[168:171], v[72:75], v[144:147]
	s_nop 3
	ds_read_b128 v[44:47], v138 offset:384
	ds_read_b128 v[48:51], v138 offset:8832
	ds_read_b128 v[52:55], v138 offset:17280
	ds_read_b128 v[56:59], v138 offset:25728
	ds_read_b128 v[60:63], v138 offset:448
	ds_read_b128 v[64:67], v138 offset:8896
	ds_read_b128 v[68:71], v138 offset:17344
	ds_read_b128 v[72:75], v138 offset:25792
	s_waitcnt lgkmcnt(8)
	v_mfma_f32_16x16x32_bf16 v[76:79], v[4:7], v[12:15], 0
	v_mfma_f32_16x16x32_bf16 v[76:79], v[8:11], v[16:19], v[76:79]
	v_mfma_f32_16x16x32_bf16 v[84:87], v[4:7], v[20:23], 0
	v_mfma_f32_16x16x32_bf16 v[84:87], v[8:11], v[24:27], v[84:87]
	v_mfma_f32_16x16x32_bf16 v[88:91], v[4:7], v[28:31], 0
	v_mfma_f32_16x16x32_bf16 v[88:91], v[8:11], v[32:35], v[88:91]
	v_mfma_f32_16x16x32_bf16 v[96:99], v[4:7], v[36:39], 0
	v_mfma_f32_16x16x32_bf16 v[96:99], v[8:11], v[40:43], v[96:99]
	s_nop 7
	v_mul_f32_e32 v76, 0x3e000000, v76
	v_mul_f32_e32 v77, 0x3e000000, v77
	v_mul_f32_e32 v78, 0x3e000000, v78
	v_mul_f32_e32 v79, 0x3e000000, v79
	v_mul_f32_e32 v84, 0x3e000000, v84
	v_mul_f32_e32 v85, 0x3e000000, v85
	v_mul_f32_e32 v86, 0x3e000000, v86
	v_mul_f32_e32 v87, 0x3e000000, v87
	v_mul_f32_e32 v88, 0x3e000000, v88
	v_mul_f32_e32 v89, 0x3e000000, v89
	v_mul_f32_e32 v90, 0x3e000000, v90
	v_mul_f32_e32 v91, 0x3e000000, v91
	v_mul_f32_e32 v96, 0x3e000000, v96
	v_mul_f32_e32 v97, 0x3e000000, v97
	v_mul_f32_e32 v98, 0x3e000000, v98
	v_mul_f32_e32 v99, 0x3e000000, v99
	v_max3_f32 v184, v76, v84, v88
	v_max_f32_e32 v184, v184, v96
	v_max3_f32 v185, v77, v85, v89
	v_max_f32_e32 v185, v185, v97
	v_max3_f32 v186, v78, v86, v90
	v_max_f32_e32 v186, v186, v98
	v_max3_f32 v187, v79, v87, v91
	v_max_f32_e32 v187, v187, v99
	s_nop 0
	v_max_f32_dpp v184, v184, v184 quad_perm:[1,0,3,2] row_mask:0xf bank_mask:0xf
	v_max_f32_dpp v185, v185, v185 quad_perm:[1,0,3,2] row_mask:0xf bank_mask:0xf
	v_max_f32_dpp v186, v186, v186 quad_perm:[1,0,3,2] row_mask:0xf bank_mask:0xf
	v_max_f32_dpp v187, v187, v187 quad_perm:[1,0,3,2] row_mask:0xf bank_mask:0xf
	v_max_f32_dpp v184, v184, v184 quad_perm:[2,3,0,1] row_mask:0xf bank_mask:0xf
	v_max_f32_dpp v185, v185, v185 quad_perm:[2,3,0,1] row_mask:0xf bank_mask:0xf
	v_max_f32_dpp v186, v186, v186 quad_perm:[2,3,0,1] row_mask:0xf bank_mask:0xf
	v_max_f32_dpp v187, v187, v187 quad_perm:[2,3,0,1] row_mask:0xf bank_mask:0xf
	v_max_f32_dpp v184, v184, v184 row_half_mirror row_mask:0xf bank_mask:0xf
	v_max_f32_dpp v185, v185, v185 row_half_mirror row_mask:0xf bank_mask:0xf
	v_max_f32_dpp v186, v186, v186 row_half_mirror row_mask:0xf bank_mask:0xf
	v_max_f32_dpp v187, v187, v187 row_half_mirror row_mask:0xf bank_mask:0xf
	v_max_f32_dpp v184, v184, v184 row_ror:8 row_mask:0xf bank_mask:0xf
	v_max_f32_dpp v185, v185, v185 row_ror:8 row_mask:0xf bank_mask:0xf
	v_max_f32_dpp v186, v186, v186 row_ror:8 row_mask:0xf bank_mask:0xf
	v_max_f32_dpp v187, v187, v187 row_ror:8 row_mask:0xf bank_mask:0xf
	v_max_f32_e32 v184, v172, v184
	v_max_f32_e32 v185, v173, v185
	v_max_f32_e32 v186, v174, v186
	v_max_f32_e32 v187, v175, v187
	v_sub_f32_e32 v180, v172, v184
	v_mov_b32_e32 v172, v184
	v_sub_f32_e32 v181, v173, v185
	v_mov_b32_e32 v173, v185
	v_sub_f32_e32 v182, v174, v186
	v_mov_b32_e32 v174, v186
	v_sub_f32_e32 v183, v175, v187
	v_mov_b32_e32 v175, v187
	v_mul_f32_e32 v180, 0x3fb8aa3b, v180
	v_mul_f32_e32 v181, 0x3fb8aa3b, v181
	v_mul_f32_e32 v182, 0x3fb8aa3b, v182
	v_mul_f32_e32 v183, 0x3fb8aa3b, v183
	v_exp_f32_e32 v180, v180
	v_exp_f32_e32 v181, v181
	v_exp_f32_e32 v182, v182
	v_exp_f32_e32 v183, v183
	v_mul_f32_e32 v184, 0x3fb8aa3b, v172
	v_mul_f32_e32 v185, 0x3fb8aa3b, v173
	v_mul_f32_e32 v186, 0x3fb8aa3b, v174
	v_mul_f32_e32 v187, 0x3fb8aa3b, v175
	v_fma_f32 v76, v76, v222, -v184
	v_fma_f32 v77, v77, v222, -v185
	v_fma_f32 v78, v78, v222, -v186
	v_fma_f32 v79, v79, v222, -v187
	v_fma_f32 v84, v84, v222, -v184
	v_fma_f32 v85, v85, v222, -v185
	v_fma_f32 v86, v86, v222, -v186
	v_fma_f32 v87, v87, v222, -v187
	v_fma_f32 v88, v88, v222, -v184
	v_fma_f32 v89, v89, v222, -v185
	v_fma_f32 v90, v90, v222, -v186
	v_fma_f32 v91, v91, v222, -v187
	v_fma_f32 v96, v96, v222, -v184
	v_fma_f32 v97, v97, v222, -v185
	v_fma_f32 v98, v98, v222, -v186
	v_fma_f32 v99, v99, v222, -v187
	v_exp_f32_e32 v76, v76
	v_exp_f32_e32 v77, v77
	v_exp_f32_e32 v78, v78
	v_exp_f32_e32 v79, v79
	v_exp_f32_e32 v84, v84
	v_exp_f32_e32 v85, v85
	v_exp_f32_e32 v86, v86
	v_exp_f32_e32 v87, v87
	v_exp_f32_e32 v88, v88
	v_exp_f32_e32 v89, v89
	v_exp_f32_e32 v90, v90
	v_exp_f32_e32 v91, v91
	v_exp_f32_e32 v96, v96
	v_exp_f32_e32 v97, v97
	v_exp_f32_e32 v98, v98
	v_exp_f32_e32 v99, v99
	s_nop 0
	v_mul_f32_e32 v176, v176, v180
	v_mul_f32_e32 v177, v177, v181
	v_mul_f32_e32 v178, v178, v182
	v_mul_f32_e32 v179, v179, v183
	v_add_f32_e32 v176, v176, v76
	v_add_f32_e32 v177, v177, v77
	v_add_f32_e32 v178, v178, v78
	v_add_f32_e32 v179, v179, v79
	v_add_f32_e32 v176, v176, v84
	v_add_f32_e32 v177, v177, v85
	v_add_f32_e32 v178, v178, v86
	v_add_f32_e32 v179, v179, v87
	v_add_f32_e32 v176, v176, v88
	v_add_f32_e32 v177, v177, v89
	v_add_f32_e32 v178, v178, v90
	v_add_f32_e32 v179, v179, v91
	v_add_f32_e32 v176, v176, v96
	v_add_f32_e32 v177, v177, v97
	v_add_f32_e32 v178, v178, v98
	v_add_f32_e32 v179, v179, v99
	v_cvt_pk_bf16_f32 v80, v76, v84
	ds_write_b16 v188, v80 offset:0
	ds_write_b16_d16_hi v188, v80 offset:32
	v_cvt_pk_bf16_f32 v81, v77, v85
	ds_write_b16 v188, v81 offset:160
	ds_write_b16_d16_hi v188, v81 offset:192
	v_cvt_pk_bf16_f32 v124, v78, v86
	ds_write_b16 v188, v124 offset:320
	ds_write_b16_d16_hi v188, v124 offset:352
	v_cvt_pk_bf16_f32 v126, v79, v87
	ds_write_b16 v188, v126 offset:480
	ds_write_b16_d16_hi v188, v126 offset:512
	v_cvt_pk_bf16_f32 v80, v88, v96
	ds_write_b16 v188, v80 offset:64
	ds_write_b16_d16_hi v188, v80 offset:96
	v_cvt_pk_bf16_f32 v81, v89, v97
	ds_write_b16 v188, v81 offset:224
	ds_write_b16_d16_hi v188, v81 offset:256
	v_cvt_pk_bf16_f32 v124, v90, v98
	ds_write_b16 v188, v124 offset:384
	ds_write_b16_d16_hi v188, v124 offset:416
	v_cvt_pk_bf16_f32 v126, v91, v99
	ds_write_b16 v188, v126 offset:544
	ds_write_b16_d16_hi v188, v126 offset:576
	v_mul_f32_e32 v100, v100, v180
	v_mul_f32_e32 v101, v101, v181
	v_mul_f32_e32 v102, v102, v182
	v_mul_f32_e32 v103, v103, v183
	v_mul_f32_e32 v132, v132, v180
	v_mul_f32_e32 v133, v133, v181
	v_mul_f32_e32 v134, v134, v182
	v_mul_f32_e32 v135, v135, v183
	v_mul_f32_e32 v140, v140, v180
	v_mul_f32_e32 v141, v141, v181
	v_mul_f32_e32 v142, v142, v182
	v_mul_f32_e32 v143, v143, v183
	v_mul_f32_e32 v144, v144, v180
	v_mul_f32_e32 v145, v145, v181
	v_mul_f32_e32 v146, v146, v182
	v_mul_f32_e32 v147, v147, v183
	s_waitcnt lgkmcnt(0)
	ds_read_b128 v[164:167], v191 offset:0
	ds_read_b128 v[168:171], v191 offset:64
	s_waitcnt lgkmcnt(0)
	v_mfma_f32_16x16x32_bf16 v[100:103], v[164:167], v[44:47], v[100:103]
	v_mfma_f32_16x16x32_bf16 v[132:135], v[164:167], v[48:51], v[132:135]
	v_mfma_f32_16x16x32_bf16 v[140:143], v[164:167], v[52:55], v[140:143]
	v_mfma_f32_16x16x32_bf16 v[144:147], v[164:167], v[56:59], v[144:147]
	v_mfma_f32_16x16x32_bf16 v[100:103], v[168:171], v[60:63], v[100:103]
	v_mfma_f32_16x16x32_bf16 v[132:135], v[168:171], v[64:67], v[132:135]
	v_mfma_f32_16x16x32_bf16 v[140:143], v[168:171], v[68:71], v[140:143]
	v_mfma_f32_16x16x32_bf16 v[144:147], v[168:171], v[72:75], v[144:147]
	s_nop 3
	s_nop 7
	v_add_f32_dpp v176, v176, v176 quad_perm:[1,0,3,2] row_mask:0xf bank_mask:0xf bound_ctrl:1
	v_add_f32_dpp v177, v177, v177 quad_perm:[1,0,3,2] row_mask:0xf bank_mask:0xf bound_ctrl:1
	v_add_f32_dpp v178, v178, v178 quad_perm:[1,0,3,2] row_mask:0xf bank_mask:0xf bound_ctrl:1
	v_add_f32_dpp v179, v179, v179 quad_perm:[1,0,3,2] row_mask:0xf bank_mask:0xf bound_ctrl:1
	v_add_f32_dpp v176, v176, v176 quad_perm:[2,3,0,1] row_mask:0xf bank_mask:0xf bound_ctrl:1
	v_add_f32_dpp v177, v177, v177 quad_perm:[2,3,0,1] row_mask:0xf bank_mask:0xf bound_ctrl:1
	v_add_f32_dpp v178, v178, v178 quad_perm:[2,3,0,1] row_mask:0xf bank_mask:0xf bound_ctrl:1
	v_add_f32_dpp v179, v179, v179 quad_perm:[2,3,0,1] row_mask:0xf bank_mask:0xf bound_ctrl:1
	v_add_f32_dpp v176, v176, v176 row_half_mirror row_mask:0xf bank_mask:0xf bound_ctrl:1
	v_add_f32_dpp v177, v177, v177 row_half_mirror row_mask:0xf bank_mask:0xf bound_ctrl:1
	v_add_f32_dpp v178, v178, v178 row_half_mirror row_mask:0xf bank_mask:0xf bound_ctrl:1
	v_add_f32_dpp v179, v179, v179 row_half_mirror row_mask:0xf bank_mask:0xf bound_ctrl:1
	v_add_f32_dpp v176, v176, v176 row_ror:8 row_mask:0xf bank_mask:0xf bound_ctrl:1
	v_add_f32_dpp v177, v177, v177 row_ror:8 row_mask:0xf bank_mask:0xf bound_ctrl:1
	v_add_f32_dpp v178, v178, v178 row_ror:8 row_mask:0xf bank_mask:0xf bound_ctrl:1
	v_add_f32_dpp v179, v179, v179 row_ror:8 row_mask:0xf bank_mask:0xf bound_ctrl:1
	v_rcp_f32_e32 v180, v176
	v_rcp_f32_e32 v181, v177
	v_rcp_f32_e32 v182, v178
	v_rcp_f32_e32 v183, v179
	s_nop 0
	v_fma_f32 v184, -v176, v180, 1.0
	v_fma_f32 v180, v184, v180, v180
	v_fma_f32 v185, -v177, v181, 1.0
	v_fma_f32 v181, v185, v181, v181
	v_fma_f32 v186, -v178, v182, 1.0
	v_fma_f32 v182, v186, v182, v182
	v_fma_f32 v187, -v179, v183, 1.0
	v_fma_f32 v183, v187, v183, v183
	v_add_u32_e32 v80, 0x0, v208
	v_add_u32_e32 v81, 0x1000, v208
	v_add_u32_e32 v124, 0x2000, v208
	v_add_u32_e32 v126, 0x3000, v208
	v_mul_f32_e32 v100, v100, v180
	v_cvt_pk_bf16_f32 v100, v100, v100
	global_store_short v80, v100, s[20:21] offset:0
	v_mul_f32_e32 v101, v101, v181
	v_cvt_pk_bf16_f32 v101, v101, v101
	global_store_short v81, v101, s[20:21] offset:0
	v_mul_f32_e32 v102, v102, v182
	v_cvt_pk_bf16_f32 v102, v102, v102
	global_store_short v124, v102, s[20:21] offset:0
	v_mul_f32_e32 v103, v103, v183
	v_cvt_pk_bf16_f32 v103, v103, v103
	global_store_short v126, v103, s[20:21] offset:0
	v_mul_f32_e32 v132, v132, v180
	v_cvt_pk_bf16_f32 v132, v132, v132
	global_store_short v80, v132, s[20:21] offset:32
	v_mul_f32_e32 v133, v133, v181
	v_cvt_pk_bf16_f32 v133, v133, v133
	global_store_short v81, v133, s[20:21] offset:32
	v_mul_f32_e32 v134, v134, v182
	v_cvt_pk_bf16_f32 v134, v134, v134
	global_store_short v124, v134, s[20:21] offset:32
	v_mul_f32_e32 v135, v135, v183
	v_cvt_pk_bf16_f32 v135, v135, v135
	global_store_short v126, v135, s[20:21] offset:32
	v_mul_f32_e32 v140, v140, v180
	v_cvt_pk_bf16_f32 v140, v140, v140
	global_store_short v80, v140, s[20:21] offset:64
	v_mul_f32_e32 v141, v141, v181
	v_cvt_pk_bf16_f32 v141, v141, v141
	global_store_short v81, v141, s[20:21] offset:64
	v_mul_f32_e32 v142, v142, v182
	v_cvt_pk_bf16_f32 v142, v142, v142
	global_store_short v124, v142, s[20:21] offset:64
	v_mul_f32_e32 v143, v143, v183
	v_cvt_pk_bf16_f32 v143, v143, v143
	global_store_short v126, v143, s[20:21] offset:64
	v_mul_f32_e32 v144, v144, v180
	v_cvt_pk_bf16_f32 v144, v144, v144
	global_store_short v80, v144, s[20:21] offset:96
	v_mul_f32_e32 v145, v145, v181
	v_cvt_pk_bf16_f32 v145, v145, v145
	global_store_short v81, v145, s[20:21] offset:96
	v_mul_f32_e32 v146, v146, v182
	v_cvt_pk_bf16_f32 v146, v146, v146
	global_store_short v124, v146, s[20:21] offset:96
	v_mul_f32_e32 v147, v147, v183
	v_cvt_pk_bf16_f32 v147, v147, v147
	global_store_short v126, v147, s[20:21] offset:96
	s_add_i32 s89, s89, 1
	s_addk_i32 s88, 0x800
	s_cmp_eq_u32 s89, 16
	s_cbranch_scc1 .LBB0_719
	s_branch .LBB0_459
